# up-projection epilogue rewritten by hand: DPP-fused conv FMAs, 16-byte act stores, weights prefetched before the exchange barrier
# speedup vs baseline: 1.0336x; 1.0183x over previous
;     __device__ __forceinline__ void operator()(const f32x4 (&acc)[2][2][4][2], const Unit& u, int wr, int wc, int fr, int fq) const {
;     ...
;         const int colj = u.pn * 128 + wc * 32 + 8 * fq;
;         float* hb = halo + (size_t)(u.pm * 22 + u.pn) * 1024 + wc * 32 + 8 * fq;
; #pragma unroll
;         for (int n = 0; n < 2; ++n) {
;             f32x4 wgt[3][2];
; #pragma unroll
;             for (int i = 0; i < 3; ++i)
; #pragma unroll
;                 for (int bj = 0; bj < 2; ++bj) wgt[i][bj] = *(const f32x4*)(cw + i * 5632 + bj * 2816 + colj + 4 * n);
; #pragma unroll
;             for (int ai = 0; ai < 2; ++ai) {
;                 const bool top = (wr == 0 && ai == 0);
;                 f32x4 h1[2], h2[2];
;                 const float* sx = xch + (wr == 1 ? wc : 4 + wc) * 256 + (wr == 1 ? ai * 2 : 0) * 64 + fq * 8 + n * 4;
; #pragma unroll
;                 for (int bj = 0; bj < 2; ++bj) {
;                     if (!top) { h2[bj] = *(const f32x4*)(sx + bj * 32); h1[bj] = *(const f32x4*)(sx + 64 + bj * 32); }
;                     else { h2[bj] = (f32x4){0.f, 0.f, 0.f, 0.f}; h1[bj] = (f32x4){0.f, 0.f, 0.f, 0.f}; }
;                 }
; #pragma unroll
;                 for (int m = 0; m < 4; ++m) {
;                     float cv[2][4];
; #pragma unroll
;                     for (int bj = 0; bj < 2; ++bj)
; #pragma unroll
;                         for (int e = 0; e < 4; ++e) {
;                             const float x = acc[ai][bj][m][n][e];
;                             const float r1s = dpp_ror1(x), r2s = dpp_ror2(x);
;                             float r1p, r2p;
;                             if (m > 0) { const float xp = acc[ai][bj][m > 0 ? m - 1 : 0][n][e]; r1p = dpp_ror1(xp); r2p = dpp_ror2(xp); }
;                             else { r1p = h1[bj][e]; r2p = (fr == 0) ? h2[bj][e] : h1[bj][e]; }
;                             const float p1 = (fr == 0) ? r1p : r1s, p2 = (fr < 2) ? r2p : r2s;
;                             cv[bj][e] = wgt[0][bj][e] * p2 + wgt[1][bj][e] * p1 + wgt[2][bj][e] * x;
;                         }
;                     const int r = u.pm * BM + ai * HALF + wr * 64 + m * 16 + fr;
;                     if (top && m == 0 && fr < 2) {
; #pragma unroll
;                         for (int bj = 0; bj < 2; ++bj) *(f32x4*)(hb + fr * 256 + bj * 128 + 4 * n) = acc[0][bj][0][n];
;                     } else {
.LBB0_72:
	s_or_b64 exec, exec, s[14:15]
	v_lshl_or_b32 v190, s78, 7, v206
	v_lshlrev_b32_e32 v253, 2, v190
	v_lshl_add_u32 v252, s92, 8, v194
	s_movk_i32 s1, 0x1600
	v_mul_lo_u32 v252, v252, s1
	v_lshl_add_u32 v252, v190, 1, v252
	s_add_u32 s56, s24, 0x0
	s_addc_u32 s57, s25, 0
	global_load_dwordx4 v[98:101], v253, s[56:57]
	s_add_u32 s56, s24, 0x2c00
	s_addc_u32 s57, s25, 0
	global_load_dwordx4 v[102:105], v253, s[56:57]
	s_add_u32 s56, s24, 0x5800
	s_addc_u32 s57, s25, 0
	global_load_dwordx4 v[106:109], v253, s[56:57]
	s_add_u32 s56, s24, 0x8400
	s_addc_u32 s57, s25, 0
	global_load_dwordx4 v[110:113], v253, s[56:57]
	s_add_u32 s56, s24, 0xb000
	s_addc_u32 s57, s25, 0
	global_load_dwordx4 v[114:117], v253, s[56:57]
	s_add_u32 s56, s24, 0xdc00
	s_addc_u32 s57, s25, 0
	global_load_dwordx4 v[118:121], v253, s[56:57]
	s_waitcnt lgkmcnt(0)
	s_barrier
	s_mul_i32 s1, s92, 22
	s_add_i32 s1, s1, s78
	s_lshl_b32 s56, s1, 12
	s_mov_b32 s57, 0
	s_and_b64 vcc, exec, s[62:63]
	s_cbranch_vccnz .Lup_halo_bot
	v_lshl_add_u64 v[240:241], v[184:185], 0, s[56:57]
	s_and_b64 exec, exec, s[10:11]
	global_store_dwordx4 v[240:241], v[150:153], off
	global_store_dwordx4 v[240:241], v[70:73], off offset:16
	global_store_dwordx4 v[240:241], v[146:149], off offset:512
	global_store_dwordx4 v[240:241], v[66:69], off offset:528
	s_mov_b64 exec, -1
	s_branch .Lup_halo_done
.Lup_halo_bot:
	s_sub_u32 s56, s56, 0x3000
	s_subb_u32 s57, s57, 0
	v_lshl_add_u64 v[240:241], v[184:185], 0, s[56:57]
	s_and_b64 exec, exec, s[6:7]
	global_store_dwordx4 v[240:241], v[14:17], off
	global_store_dwordx4 v[240:241], v[10:13], off offset:16
	global_store_dwordx4 v[240:241], v[6:9], off offset:512
	global_store_dwordx4 v[240:241], v[2:5], off offset:528
	s_mov_b64 exec, -1
.Lup_halo_done:
	s_waitcnt vmcnt(4)
	v_cndmask_b32_e64 v154, 0, v106, s[8:9]
	v_cndmask_b32_e64 v155, 0, v107, s[8:9]
	v_cndmask_b32_e64 v156, 0, v108, s[8:9]
	v_cndmask_b32_e64 v157, 0, v109, s[8:9]
	v_cndmask_b32_e64 v158, 0, v110, s[8:9]
	v_cndmask_b32_e64 v159, 0, v111, s[8:9]
	v_cndmask_b32_e64 v160, 0, v112, s[8:9]
	v_cndmask_b32_e64 v161, 0, v113, s[8:9]
	v_cndmask_b32_e64 v162, 0, v98, s[10:11]
	v_cndmask_b32_e64 v163, 0, v99, s[10:11]
	v_cndmask_b32_e64 v164, 0, v100, s[10:11]
	v_cndmask_b32_e64 v165, 0, v101, s[10:11]
	v_cndmask_b32_e64 v166, 0, v102, s[10:11]
	v_cndmask_b32_e64 v167, 0, v103, s[10:11]
	v_cndmask_b32_e64 v168, 0, v104, s[10:11]
	v_cndmask_b32_e64 v169, 0, v105, s[10:11]
	s_and_b64 vcc, exec, s[62:63]
	s_cbranch_vccz .Lup_n0a0_top
	v_and_b32_e32 v240, 15, v194
	v_add_u32_e32 v240, 1, v240
	v_and_b32_e32 v240, 16, v240
	v_lshl_add_u32 v240, v240, 4, v204
	ds_read_b128 v[190:193], v240 offset:0
	ds_read_b128 v[208:211], v240 offset:128
	s_waitcnt lgkmcnt(0)
	v_mul_f32_e32 v240, v114, v150
	v_mul_f32_e32 v241, v115, v151
	v_mul_f32_e32 v242, v116, v152
	v_mul_f32_e32 v243, v117, v153
	v_fmac_f32_dpp v240, v150, v106 row_shr:1 row_mask:0xf bank_mask:0xf bound_ctrl:1
	v_fmac_f32_dpp v241, v151, v107 row_shr:1 row_mask:0xf bank_mask:0xf bound_ctrl:1
	v_fmac_f32_dpp v242, v152, v108 row_shr:1 row_mask:0xf bank_mask:0xf bound_ctrl:1
	v_fmac_f32_dpp v243, v153, v109 row_shr:1 row_mask:0xf bank_mask:0xf bound_ctrl:1
	v_fmac_f32_dpp v240, v150, v98 row_shr:2 row_mask:0xf bank_mask:0xf bound_ctrl:1
	v_fmac_f32_dpp v241, v151, v99 row_shr:2 row_mask:0xf bank_mask:0xf bound_ctrl:1
	v_fmac_f32_dpp v242, v152, v100 row_shr:2 row_mask:0xf bank_mask:0xf bound_ctrl:1
	v_fmac_f32_dpp v243, v153, v101 row_shr:2 row_mask:0xf bank_mask:0xf bound_ctrl:1
	v_fmac_f32_dpp v240, v190, v154 row_ror:1 row_mask:0xf bank_mask:0xf
	v_fmac_f32_dpp v241, v191, v155 row_ror:1 row_mask:0xf bank_mask:0xf
	v_fmac_f32_dpp v242, v192, v156 row_ror:1 row_mask:0xf bank_mask:0xf
	v_fmac_f32_dpp v243, v193, v157 row_ror:1 row_mask:0xf bank_mask:0xf
	v_fmac_f32_dpp v240, v190, v162 row_ror:2 row_mask:0xf bank_mask:0xf
	v_fmac_f32_dpp v241, v191, v163 row_ror:2 row_mask:0xf bank_mask:0xf
	v_fmac_f32_dpp v242, v192, v164 row_ror:2 row_mask:0xf bank_mask:0xf
	v_fmac_f32_dpp v243, v193, v165 row_ror:2 row_mask:0xf bank_mask:0xf
	v_mul_f32_e32 v244, v118, v146
	v_mul_f32_e32 v245, v119, v147
	v_mul_f32_e32 v246, v120, v148
	v_mul_f32_e32 v247, v121, v149
	v_fmac_f32_dpp v244, v146, v110 row_shr:1 row_mask:0xf bank_mask:0xf bound_ctrl:1
	v_fmac_f32_dpp v245, v147, v111 row_shr:1 row_mask:0xf bank_mask:0xf bound_ctrl:1
	v_fmac_f32_dpp v246, v148, v112 row_shr:1 row_mask:0xf bank_mask:0xf bound_ctrl:1
	v_fmac_f32_dpp v247, v149, v113 row_shr:1 row_mask:0xf bank_mask:0xf bound_ctrl:1
	v_fmac_f32_dpp v244, v146, v102 row_shr:2 row_mask:0xf bank_mask:0xf bound_ctrl:1
	v_fmac_f32_dpp v245, v147, v103 row_shr:2 row_mask:0xf bank_mask:0xf bound_ctrl:1
	v_fmac_f32_dpp v246, v148, v104 row_shr:2 row_mask:0xf bank_mask:0xf bound_ctrl:1
	v_fmac_f32_dpp v247, v149, v105 row_shr:2 row_mask:0xf bank_mask:0xf bound_ctrl:1
	v_fmac_f32_dpp v244, v208, v158 row_ror:1 row_mask:0xf bank_mask:0xf
	v_fmac_f32_dpp v245, v209, v159 row_ror:1 row_mask:0xf bank_mask:0xf
	v_fmac_f32_dpp v246, v210, v160 row_ror:1 row_mask:0xf bank_mask:0xf
	v_fmac_f32_dpp v247, v211, v161 row_ror:1 row_mask:0xf bank_mask:0xf
	v_fmac_f32_dpp v244, v208, v166 row_ror:2 row_mask:0xf bank_mask:0xf
	v_fmac_f32_dpp v245, v209, v167 row_ror:2 row_mask:0xf bank_mask:0xf
	v_fmac_f32_dpp v246, v210, v168 row_ror:2 row_mask:0xf bank_mask:0xf
	v_fmac_f32_dpp v247, v211, v169 row_ror:2 row_mask:0xf bank_mask:0xf
	v_mul_f32_e32 v248, 0xbfb8aa3b, v240
	v_mul_f32_e32 v249, 0xbfb8aa3b, v241
	v_mul_f32_e32 v250, 0xbfb8aa3b, v242
	v_mul_f32_e32 v251, 0xbfb8aa3b, v243
	v_exp_f32_e32 v248, v248
	v_exp_f32_e32 v249, v249
	v_exp_f32_e32 v250, v250
	v_exp_f32_e32 v251, v251
	v_add_f32_e32 v248, 1.0, v248
	v_add_f32_e32 v249, 1.0, v249
	v_add_f32_e32 v250, 1.0, v250
	v_add_f32_e32 v251, 1.0, v251
	v_rcp_f32_e32 v248, v248
	v_rcp_f32_e32 v249, v249
	v_rcp_f32_e32 v250, v250
	v_rcp_f32_e32 v251, v251
	v_mul_f32_e32 v248, v240, v248
	v_mul_f32_e32 v249, v241, v249
	v_mul_f32_e32 v250, v242, v250
	v_mul_f32_e32 v251, v243, v251
	v_mul_f32_e32 v248, v248, v244
	v_mul_f32_e32 v249, v249, v245
	v_mul_f32_e32 v250, v250, v246
	v_mul_f32_e32 v251, v251, v247
	s_branch .Lup_n0a0_join
; __device__ __forceinline__ unsigned cvt_pk_bf16(float lo, float hi) { f32x2_t_ v = {lo, hi}; bf16x2_t_ b = __builtin_convertvector(v, bf16x2_t_); return __builtin_bit_cast(unsigned, b); }
; __device__ __forceinline__ float dpp_ror1(float v) { return __builtin_bit_cast(float, __builtin_amdgcn_update_dpp(0, __builtin_bit_cast(int, v), 0x121, 0xf, 0xf, false)); }
; __device__ __forceinline__ float dpp_ror2(float v) { return __builtin_bit_cast(float, __builtin_amdgcn_update_dpp(0, __builtin_bit_cast(int, v), 0x122, 0xf, 0xf, false)); }
;     __device__ __forceinline__ void operator()(const f32x4 (&acc)[2][2][4][2], const Unit& u, int wr, int wc, int fr, int fq) const {
;     ...
;                 for (int m = 0; m < 4; ++m) {
;                     float cv[2][4];
; #pragma unroll
;                     for (int bj = 0; bj < 2; ++bj)
; #pragma unroll
;                         for (int e = 0; e < 4; ++e) {
;                             const float x = acc[ai][bj][m][n][e];
;                             const float r1s = dpp_ror1(x), r2s = dpp_ror2(x);
;                             float r1p, r2p;
;                             if (m > 0) { const float xp = acc[ai][bj][m > 0 ? m - 1 : 0][n][e]; r1p = dpp_ror1(xp); r2p = dpp_ror2(xp); }
;                             else { r1p = h1[bj][e]; r2p = (fr == 0) ? h2[bj][e] : h1[bj][e]; }
;                             const float p1 = (fr == 0) ? r1p : r1s, p2 = (fr < 2) ? r2p : r2s;
;                             cv[bj][e] = wgt[0][bj][e] * p2 + wgt[1][bj][e] * p1 + wgt[2][bj][e] * x;
;                         }
;                     const int r = u.pm * BM + ai * HALF + wr * 64 + m * 16 + fr;
;                     if (top && m == 0 && fr < 2) {
; #pragma unroll
;                         for (int bj = 0; bj < 2; ++bj) *(f32x4*)(hb + fr * 256 + bj * 128 + 4 * n) = acc[0][bj][0][n];
;                     } else {
;                         float o[4];
; #pragma unroll
;                         for (int c = 0; c < 4; ++c) { const float g = cv[0][c]; o[c] = g * __builtin_amdgcn_rcpf(1.0f + __expf(-g)) * cv[1][c]; }
;                         u32x2 w; w.x = cvt_pk_bf16(o[0], o[1]); w.y = cvt_pk_bf16(o[2], o[3]);
;                         *(u32x2*)(act + (size_t)r * 2816 + colj + 4 * n) = w;
;                     }
.Lup_n0a0_top:
	v_mul_f32_e32 v240, v114, v150
	v_mul_f32_e32 v241, v115, v151
	v_mul_f32_e32 v242, v116, v152
	v_mul_f32_e32 v243, v117, v153
	v_fmac_f32_dpp v240, v150, v106 row_shr:1 row_mask:0xf bank_mask:0xf bound_ctrl:1
	v_fmac_f32_dpp v241, v151, v107 row_shr:1 row_mask:0xf bank_mask:0xf bound_ctrl:1
	v_fmac_f32_dpp v242, v152, v108 row_shr:1 row_mask:0xf bank_mask:0xf bound_ctrl:1
	v_fmac_f32_dpp v243, v153, v109 row_shr:1 row_mask:0xf bank_mask:0xf bound_ctrl:1
	v_fmac_f32_dpp v240, v150, v98 row_shr:2 row_mask:0xf bank_mask:0xf bound_ctrl:1
	v_fmac_f32_dpp v241, v151, v99 row_shr:2 row_mask:0xf bank_mask:0xf bound_ctrl:1
	v_fmac_f32_dpp v242, v152, v100 row_shr:2 row_mask:0xf bank_mask:0xf bound_ctrl:1
	v_fmac_f32_dpp v243, v153, v101 row_shr:2 row_mask:0xf bank_mask:0xf bound_ctrl:1
	v_mul_f32_e32 v244, v118, v146
	v_mul_f32_e32 v245, v119, v147
	v_mul_f32_e32 v246, v120, v148
	v_mul_f32_e32 v247, v121, v149
	v_fmac_f32_dpp v244, v146, v110 row_shr:1 row_mask:0xf bank_mask:0xf bound_ctrl:1
	v_fmac_f32_dpp v245, v147, v111 row_shr:1 row_mask:0xf bank_mask:0xf bound_ctrl:1
	v_fmac_f32_dpp v246, v148, v112 row_shr:1 row_mask:0xf bank_mask:0xf bound_ctrl:1
	v_fmac_f32_dpp v247, v149, v113 row_shr:1 row_mask:0xf bank_mask:0xf bound_ctrl:1
	v_fmac_f32_dpp v244, v146, v102 row_shr:2 row_mask:0xf bank_mask:0xf bound_ctrl:1
	v_fmac_f32_dpp v245, v147, v103 row_shr:2 row_mask:0xf bank_mask:0xf bound_ctrl:1
	v_fmac_f32_dpp v246, v148, v104 row_shr:2 row_mask:0xf bank_mask:0xf bound_ctrl:1
	v_fmac_f32_dpp v247, v149, v105 row_shr:2 row_mask:0xf bank_mask:0xf bound_ctrl:1
	v_mul_f32_e32 v248, 0xbfb8aa3b, v240
	v_mul_f32_e32 v249, 0xbfb8aa3b, v241
	v_mul_f32_e32 v250, 0xbfb8aa3b, v242
	v_mul_f32_e32 v251, 0xbfb8aa3b, v243
	v_exp_f32_e32 v248, v248
	v_exp_f32_e32 v249, v249
	v_exp_f32_e32 v250, v250
	v_exp_f32_e32 v251, v251
	v_add_f32_e32 v248, 1.0, v248
	v_add_f32_e32 v249, 1.0, v249
	v_add_f32_e32 v250, 1.0, v250
	v_add_f32_e32 v251, 1.0, v251
	v_rcp_f32_e32 v248, v248
	v_rcp_f32_e32 v249, v249
	v_rcp_f32_e32 v250, v250
	v_rcp_f32_e32 v251, v251
	v_mul_f32_e32 v248, v240, v248
	v_mul_f32_e32 v249, v241, v249
	v_mul_f32_e32 v250, v242, v250
	v_mul_f32_e32 v251, v243, v251
	v_mul_f32_e32 v248, v248, v244
	v_mul_f32_e32 v249, v249, v245
	v_mul_f32_e32 v250, v250, v246
	v_mul_f32_e32 v251, v251, v247
.Lup_n0a0_join:
	v_cvt_pk_bf16_f32 v224, v248, v249
	v_cvt_pk_bf16_f32 v225, v250, v251
	v_mul_f32_e32 v240, v114, v142
	v_mul_f32_e32 v241, v115, v143
	v_mul_f32_e32 v242, v116, v144
	v_mul_f32_e32 v243, v117, v145
	v_fmac_f32_dpp v240, v142, v106 row_shr:1 row_mask:0xf bank_mask:0xf bound_ctrl:1
	v_fmac_f32_dpp v241, v143, v107 row_shr:1 row_mask:0xf bank_mask:0xf bound_ctrl:1
	v_fmac_f32_dpp v242, v144, v108 row_shr:1 row_mask:0xf bank_mask:0xf bound_ctrl:1
	v_fmac_f32_dpp v243, v145, v109 row_shr:1 row_mask:0xf bank_mask:0xf bound_ctrl:1
	v_fmac_f32_dpp v240, v142, v98 row_shr:2 row_mask:0xf bank_mask:0xf bound_ctrl:1
	v_fmac_f32_dpp v241, v143, v99 row_shr:2 row_mask:0xf bank_mask:0xf bound_ctrl:1
	v_fmac_f32_dpp v242, v144, v100 row_shr:2 row_mask:0xf bank_mask:0xf bound_ctrl:1
	v_fmac_f32_dpp v243, v145, v101 row_shr:2 row_mask:0xf bank_mask:0xf bound_ctrl:1
	v_fmac_f32_dpp v240, v150, v154 row_ror:1 row_mask:0xf bank_mask:0xf
	v_fmac_f32_dpp v241, v151, v155 row_ror:1 row_mask:0xf bank_mask:0xf
	v_fmac_f32_dpp v242, v152, v156 row_ror:1 row_mask:0xf bank_mask:0xf
	v_fmac_f32_dpp v243, v153, v157 row_ror:1 row_mask:0xf bank_mask:0xf
	v_fmac_f32_dpp v240, v150, v162 row_ror:2 row_mask:0xf bank_mask:0xf
	v_fmac_f32_dpp v241, v151, v163 row_ror:2 row_mask:0xf bank_mask:0xf
	v_fmac_f32_dpp v242, v152, v164 row_ror:2 row_mask:0xf bank_mask:0xf
	v_fmac_f32_dpp v243, v153, v165 row_ror:2 row_mask:0xf bank_mask:0xf
	v_mul_f32_e32 v244, v118, v138
	v_mul_f32_e32 v245, v119, v139
	v_mul_f32_e32 v246, v120, v140
	v_mul_f32_e32 v247, v121, v141
	v_fmac_f32_dpp v244, v138, v110 row_shr:1 row_mask:0xf bank_mask:0xf bound_ctrl:1
	v_fmac_f32_dpp v245, v139, v111 row_shr:1 row_mask:0xf bank_mask:0xf bound_ctrl:1
	v_fmac_f32_dpp v246, v140, v112 row_shr:1 row_mask:0xf bank_mask:0xf bound_ctrl:1
	v_fmac_f32_dpp v247, v141, v113 row_shr:1 row_mask:0xf bank_mask:0xf bound_ctrl:1
	v_fmac_f32_dpp v244, v138, v102 row_shr:2 row_mask:0xf bank_mask:0xf bound_ctrl:1
	v_fmac_f32_dpp v245, v139, v103 row_shr:2 row_mask:0xf bank_mask:0xf bound_ctrl:1
	v_fmac_f32_dpp v246, v140, v104 row_shr:2 row_mask:0xf bank_mask:0xf bound_ctrl:1
	v_fmac_f32_dpp v247, v141, v105 row_shr:2 row_mask:0xf bank_mask:0xf bound_ctrl:1
	v_fmac_f32_dpp v244, v146, v158 row_ror:1 row_mask:0xf bank_mask:0xf
	v_fmac_f32_dpp v245, v147, v159 row_ror:1 row_mask:0xf bank_mask:0xf
	v_fmac_f32_dpp v246, v148, v160 row_ror:1 row_mask:0xf bank_mask:0xf
	v_fmac_f32_dpp v247, v149, v161 row_ror:1 row_mask:0xf bank_mask:0xf
	v_fmac_f32_dpp v244, v146, v166 row_ror:2 row_mask:0xf bank_mask:0xf
	v_fmac_f32_dpp v245, v147, v167 row_ror:2 row_mask:0xf bank_mask:0xf
	v_fmac_f32_dpp v246, v148, v168 row_ror:2 row_mask:0xf bank_mask:0xf
	v_fmac_f32_dpp v247, v149, v169 row_ror:2 row_mask:0xf bank_mask:0xf
	v_mul_f32_e32 v248, 0xbfb8aa3b, v240
	v_mul_f32_e32 v249, 0xbfb8aa3b, v241
	v_mul_f32_e32 v250, 0xbfb8aa3b, v242
	v_mul_f32_e32 v251, 0xbfb8aa3b, v243
	v_exp_f32_e32 v248, v248
	v_exp_f32_e32 v249, v249
	v_exp_f32_e32 v250, v250
	v_exp_f32_e32 v251, v251
	v_add_f32_e32 v248, 1.0, v248
	v_add_f32_e32 v249, 1.0, v249
	v_add_f32_e32 v250, 1.0, v250
	v_add_f32_e32 v251, 1.0, v251
	v_rcp_f32_e32 v248, v248
	v_rcp_f32_e32 v249, v249
	v_rcp_f32_e32 v250, v250
	v_rcp_f32_e32 v251, v251
	v_mul_f32_e32 v248, v240, v248
; __device__ __forceinline__ unsigned cvt_pk_bf16(float lo, float hi) { f32x2_t_ v = {lo, hi}; bf16x2_t_ b = __builtin_convertvector(v, bf16x2_t_); return __builtin_bit_cast(unsigned, b); }
; __device__ __forceinline__ float dpp_ror1(float v) { return __builtin_bit_cast(float, __builtin_amdgcn_update_dpp(0, __builtin_bit_cast(int, v), 0x121, 0xf, 0xf, false)); }
; __device__ __forceinline__ float dpp_ror2(float v) { return __builtin_bit_cast(float, __builtin_amdgcn_update_dpp(0, __builtin_bit_cast(int, v), 0x122, 0xf, 0xf, false)); }
;     __device__ __forceinline__ void operator()(const f32x4 (&acc)[2][2][4][2], const Unit& u, int wr, int wc, int fr, int fq) const {
;     ...
;                 for (int m = 0; m < 4; ++m) {
;                     float cv[2][4];
; #pragma unroll
;                     for (int bj = 0; bj < 2; ++bj)
; #pragma unroll
;                         for (int e = 0; e < 4; ++e) {
;                             const float x = acc[ai][bj][m][n][e];
;                             const float r1s = dpp_ror1(x), r2s = dpp_ror2(x);
;                             float r1p, r2p;
;                             if (m > 0) { const float xp = acc[ai][bj][m > 0 ? m - 1 : 0][n][e]; r1p = dpp_ror1(xp); r2p = dpp_ror2(xp); }
;                             else { r1p = h1[bj][e]; r2p = (fr == 0) ? h2[bj][e] : h1[bj][e]; }
;                             const float p1 = (fr == 0) ? r1p : r1s, p2 = (fr < 2) ? r2p : r2s;
;                             cv[bj][e] = wgt[0][bj][e] * p2 + wgt[1][bj][e] * p1 + wgt[2][bj][e] * x;
;                         }
;                     const int r = u.pm * BM + ai * HALF + wr * 64 + m * 16 + fr;
;                     if (top && m == 0 && fr < 2) {
; #pragma unroll
;                         for (int bj = 0; bj < 2; ++bj) *(f32x4*)(hb + fr * 256 + bj * 128 + 4 * n) = acc[0][bj][0][n];
;                     } else {
;                         float o[4];
; #pragma unroll
;                         for (int c = 0; c < 4; ++c) { const float g = cv[0][c]; o[c] = g * __builtin_amdgcn_rcpf(1.0f + __expf(-g)) * cv[1][c]; }
;                         u32x2 w; w.x = cvt_pk_bf16(o[0], o[1]); w.y = cvt_pk_bf16(o[2], o[3]);
;                         *(u32x2*)(act + (size_t)r * 2816 + colj + 4 * n) = w;
;                     }
	v_mul_f32_e32 v249, v241, v249
	v_mul_f32_e32 v250, v242, v250
	v_mul_f32_e32 v251, v243, v251
	v_mul_f32_e32 v248, v248, v244
	v_mul_f32_e32 v249, v249, v245
	v_mul_f32_e32 v250, v250, v246
	v_mul_f32_e32 v251, v251, v247
	v_cvt_pk_bf16_f32 v226, v248, v249
	v_cvt_pk_bf16_f32 v227, v250, v251
	v_mul_f32_e32 v240, v114, v134
	v_mul_f32_e32 v241, v115, v135
	v_mul_f32_e32 v242, v116, v136
	v_mul_f32_e32 v243, v117, v137
	v_fmac_f32_dpp v240, v134, v106 row_shr:1 row_mask:0xf bank_mask:0xf bound_ctrl:1
	v_fmac_f32_dpp v241, v135, v107 row_shr:1 row_mask:0xf bank_mask:0xf bound_ctrl:1
	v_fmac_f32_dpp v242, v136, v108 row_shr:1 row_mask:0xf bank_mask:0xf bound_ctrl:1
	v_fmac_f32_dpp v243, v137, v109 row_shr:1 row_mask:0xf bank_mask:0xf bound_ctrl:1
	v_fmac_f32_dpp v240, v134, v98 row_shr:2 row_mask:0xf bank_mask:0xf bound_ctrl:1
	v_fmac_f32_dpp v241, v135, v99 row_shr:2 row_mask:0xf bank_mask:0xf bound_ctrl:1
	v_fmac_f32_dpp v242, v136, v100 row_shr:2 row_mask:0xf bank_mask:0xf bound_ctrl:1
	v_fmac_f32_dpp v243, v137, v101 row_shr:2 row_mask:0xf bank_mask:0xf bound_ctrl:1
	v_fmac_f32_dpp v240, v142, v154 row_ror:1 row_mask:0xf bank_mask:0xf
	v_fmac_f32_dpp v241, v143, v155 row_ror:1 row_mask:0xf bank_mask:0xf
	v_fmac_f32_dpp v242, v144, v156 row_ror:1 row_mask:0xf bank_mask:0xf
	v_fmac_f32_dpp v243, v145, v157 row_ror:1 row_mask:0xf bank_mask:0xf
	v_fmac_f32_dpp v240, v142, v162 row_ror:2 row_mask:0xf bank_mask:0xf
	v_fmac_f32_dpp v241, v143, v163 row_ror:2 row_mask:0xf bank_mask:0xf
	v_fmac_f32_dpp v242, v144, v164 row_ror:2 row_mask:0xf bank_mask:0xf
	v_fmac_f32_dpp v243, v145, v165 row_ror:2 row_mask:0xf bank_mask:0xf
	v_mul_f32_e32 v244, v118, v130
	v_mul_f32_e32 v245, v119, v131
	v_mul_f32_e32 v246, v120, v132
	v_mul_f32_e32 v247, v121, v133
	v_fmac_f32_dpp v244, v130, v110 row_shr:1 row_mask:0xf bank_mask:0xf bound_ctrl:1
	v_fmac_f32_dpp v245, v131, v111 row_shr:1 row_mask:0xf bank_mask:0xf bound_ctrl:1
	v_fmac_f32_dpp v246, v132, v112 row_shr:1 row_mask:0xf bank_mask:0xf bound_ctrl:1
	v_fmac_f32_dpp v247, v133, v113 row_shr:1 row_mask:0xf bank_mask:0xf bound_ctrl:1
	v_fmac_f32_dpp v244, v130, v102 row_shr:2 row_mask:0xf bank_mask:0xf bound_ctrl:1
	v_fmac_f32_dpp v245, v131, v103 row_shr:2 row_mask:0xf bank_mask:0xf bound_ctrl:1
	v_fmac_f32_dpp v246, v132, v104 row_shr:2 row_mask:0xf bank_mask:0xf bound_ctrl:1
	v_fmac_f32_dpp v247, v133, v105 row_shr:2 row_mask:0xf bank_mask:0xf bound_ctrl:1
	v_fmac_f32_dpp v244, v138, v158 row_ror:1 row_mask:0xf bank_mask:0xf
	v_fmac_f32_dpp v245, v139, v159 row_ror:1 row_mask:0xf bank_mask:0xf
	v_fmac_f32_dpp v246, v140, v160 row_ror:1 row_mask:0xf bank_mask:0xf
	v_fmac_f32_dpp v247, v141, v161 row_ror:1 row_mask:0xf bank_mask:0xf
	v_fmac_f32_dpp v244, v138, v166 row_ror:2 row_mask:0xf bank_mask:0xf
	v_fmac_f32_dpp v245, v139, v167 row_ror:2 row_mask:0xf bank_mask:0xf
	v_fmac_f32_dpp v246, v140, v168 row_ror:2 row_mask:0xf bank_mask:0xf
	v_fmac_f32_dpp v247, v141, v169 row_ror:2 row_mask:0xf bank_mask:0xf
	v_mul_f32_e32 v248, 0xbfb8aa3b, v240
	v_mul_f32_e32 v249, 0xbfb8aa3b, v241
	v_mul_f32_e32 v250, 0xbfb8aa3b, v242
	v_mul_f32_e32 v251, 0xbfb8aa3b, v243
	v_exp_f32_e32 v248, v248
	v_exp_f32_e32 v249, v249
	v_exp_f32_e32 v250, v250
	v_exp_f32_e32 v251, v251
	v_add_f32_e32 v248, 1.0, v248
	v_add_f32_e32 v249, 1.0, v249
	v_add_f32_e32 v250, 1.0, v250
	v_add_f32_e32 v251, 1.0, v251
	v_rcp_f32_e32 v248, v248
	v_rcp_f32_e32 v249, v249
	v_rcp_f32_e32 v250, v250
	v_rcp_f32_e32 v251, v251
	v_mul_f32_e32 v248, v240, v248
	v_mul_f32_e32 v249, v241, v249
	v_mul_f32_e32 v250, v242, v250
	v_mul_f32_e32 v251, v243, v251
	v_mul_f32_e32 v248, v248, v244
	v_mul_f32_e32 v249, v249, v245
	v_mul_f32_e32 v250, v250, v246
	v_mul_f32_e32 v251, v251, v247
	v_cvt_pk_bf16_f32 v228, v248, v249
	v_cvt_pk_bf16_f32 v229, v250, v251
	v_mul_f32_e32 v240, v114, v126
	v_mul_f32_e32 v241, v115, v127
	v_mul_f32_e32 v242, v116, v128
	v_mul_f32_e32 v243, v117, v129
	v_fmac_f32_dpp v240, v126, v106 row_shr:1 row_mask:0xf bank_mask:0xf bound_ctrl:1
	v_fmac_f32_dpp v241, v127, v107 row_shr:1 row_mask:0xf bank_mask:0xf bound_ctrl:1
	v_fmac_f32_dpp v242, v128, v108 row_shr:1 row_mask:0xf bank_mask:0xf bound_ctrl:1
	v_fmac_f32_dpp v243, v129, v109 row_shr:1 row_mask:0xf bank_mask:0xf bound_ctrl:1
	v_fmac_f32_dpp v240, v126, v98 row_shr:2 row_mask:0xf bank_mask:0xf bound_ctrl:1
	v_fmac_f32_dpp v241, v127, v99 row_shr:2 row_mask:0xf bank_mask:0xf bound_ctrl:1
	v_fmac_f32_dpp v242, v128, v100 row_shr:2 row_mask:0xf bank_mask:0xf bound_ctrl:1
	v_fmac_f32_dpp v243, v129, v101 row_shr:2 row_mask:0xf bank_mask:0xf bound_ctrl:1
	v_fmac_f32_dpp v240, v134, v154 row_ror:1 row_mask:0xf bank_mask:0xf
	v_fmac_f32_dpp v241, v135, v155 row_ror:1 row_mask:0xf bank_mask:0xf
	v_fmac_f32_dpp v242, v136, v156 row_ror:1 row_mask:0xf bank_mask:0xf
	v_fmac_f32_dpp v243, v137, v157 row_ror:1 row_mask:0xf bank_mask:0xf
	v_fmac_f32_dpp v240, v134, v162 row_ror:2 row_mask:0xf bank_mask:0xf
	v_fmac_f32_dpp v241, v135, v163 row_ror:2 row_mask:0xf bank_mask:0xf
	v_fmac_f32_dpp v242, v136, v164 row_ror:2 row_mask:0xf bank_mask:0xf
	v_fmac_f32_dpp v243, v137, v165 row_ror:2 row_mask:0xf bank_mask:0xf
	v_mul_f32_e32 v244, v118, v122
	v_mul_f32_e32 v245, v119, v123
	v_mul_f32_e32 v246, v120, v124
	v_mul_f32_e32 v247, v121, v125
	v_fmac_f32_dpp v244, v122, v110 row_shr:1 row_mask:0xf bank_mask:0xf bound_ctrl:1
	v_fmac_f32_dpp v245, v123, v111 row_shr:1 row_mask:0xf bank_mask:0xf bound_ctrl:1
	v_fmac_f32_dpp v246, v124, v112 row_shr:1 row_mask:0xf bank_mask:0xf bound_ctrl:1
	v_fmac_f32_dpp v247, v125, v113 row_shr:1 row_mask:0xf bank_mask:0xf bound_ctrl:1
; __device__ __forceinline__ unsigned cvt_pk_bf16(float lo, float hi) { f32x2_t_ v = {lo, hi}; bf16x2_t_ b = __builtin_convertvector(v, bf16x2_t_); return __builtin_bit_cast(unsigned, b); }
; __device__ __forceinline__ float dpp_ror1(float v) { return __builtin_bit_cast(float, __builtin_amdgcn_update_dpp(0, __builtin_bit_cast(int, v), 0x121, 0xf, 0xf, false)); }
; __device__ __forceinline__ float dpp_ror2(float v) { return __builtin_bit_cast(float, __builtin_amdgcn_update_dpp(0, __builtin_bit_cast(int, v), 0x122, 0xf, 0xf, false)); }
;     __device__ __forceinline__ void operator()(const f32x4 (&acc)[2][2][4][2], const Unit& u, int wr, int wc, int fr, int fq) const {
;     ...
;                 for (int m = 0; m < 4; ++m) {
;                     float cv[2][4];
; #pragma unroll
;                     for (int bj = 0; bj < 2; ++bj)
; #pragma unroll
;                         for (int e = 0; e < 4; ++e) {
;                             const float x = acc[ai][bj][m][n][e];
;                             const float r1s = dpp_ror1(x), r2s = dpp_ror2(x);
;                             float r1p, r2p;
;                             if (m > 0) { const float xp = acc[ai][bj][m > 0 ? m - 1 : 0][n][e]; r1p = dpp_ror1(xp); r2p = dpp_ror2(xp); }
;                             else { r1p = h1[bj][e]; r2p = (fr == 0) ? h2[bj][e] : h1[bj][e]; }
;                             const float p1 = (fr == 0) ? r1p : r1s, p2 = (fr < 2) ? r2p : r2s;
;                             cv[bj][e] = wgt[0][bj][e] * p2 + wgt[1][bj][e] * p1 + wgt[2][bj][e] * x;
;                         }
;                     const int r = u.pm * BM + ai * HALF + wr * 64 + m * 16 + fr;
;                     if (top && m == 0 && fr < 2) {
; #pragma unroll
;                         for (int bj = 0; bj < 2; ++bj) *(f32x4*)(hb + fr * 256 + bj * 128 + 4 * n) = acc[0][bj][0][n];
;                     } else {
;                         float o[4];
; #pragma unroll
;                         for (int c = 0; c < 4; ++c) { const float g = cv[0][c]; o[c] = g * __builtin_amdgcn_rcpf(1.0f + __expf(-g)) * cv[1][c]; }
;                         u32x2 w; w.x = cvt_pk_bf16(o[0], o[1]); w.y = cvt_pk_bf16(o[2], o[3]);
;                         *(u32x2*)(act + (size_t)r * 2816 + colj + 4 * n) = w;
;                     }
	v_fmac_f32_dpp v244, v122, v102 row_shr:2 row_mask:0xf bank_mask:0xf bound_ctrl:1
	v_fmac_f32_dpp v245, v123, v103 row_shr:2 row_mask:0xf bank_mask:0xf bound_ctrl:1
	v_fmac_f32_dpp v246, v124, v104 row_shr:2 row_mask:0xf bank_mask:0xf bound_ctrl:1
	v_fmac_f32_dpp v247, v125, v105 row_shr:2 row_mask:0xf bank_mask:0xf bound_ctrl:1
	v_fmac_f32_dpp v244, v130, v158 row_ror:1 row_mask:0xf bank_mask:0xf
	v_fmac_f32_dpp v245, v131, v159 row_ror:1 row_mask:0xf bank_mask:0xf
	v_fmac_f32_dpp v246, v132, v160 row_ror:1 row_mask:0xf bank_mask:0xf
	v_fmac_f32_dpp v247, v133, v161 row_ror:1 row_mask:0xf bank_mask:0xf
	v_fmac_f32_dpp v244, v130, v166 row_ror:2 row_mask:0xf bank_mask:0xf
	v_fmac_f32_dpp v245, v131, v167 row_ror:2 row_mask:0xf bank_mask:0xf
	v_fmac_f32_dpp v246, v132, v168 row_ror:2 row_mask:0xf bank_mask:0xf
	v_fmac_f32_dpp v247, v133, v169 row_ror:2 row_mask:0xf bank_mask:0xf
	v_mul_f32_e32 v248, 0xbfb8aa3b, v240
	v_mul_f32_e32 v249, 0xbfb8aa3b, v241
	v_mul_f32_e32 v250, 0xbfb8aa3b, v242
	v_mul_f32_e32 v251, 0xbfb8aa3b, v243
	v_exp_f32_e32 v248, v248
	v_exp_f32_e32 v249, v249
	v_exp_f32_e32 v250, v250
	v_exp_f32_e32 v251, v251
	v_add_f32_e32 v248, 1.0, v248
	v_add_f32_e32 v249, 1.0, v249
	v_add_f32_e32 v250, 1.0, v250
	v_add_f32_e32 v251, 1.0, v251
	v_rcp_f32_e32 v248, v248
	v_rcp_f32_e32 v249, v249
	v_rcp_f32_e32 v250, v250
	v_rcp_f32_e32 v251, v251
	v_mul_f32_e32 v248, v240, v248
	v_mul_f32_e32 v249, v241, v249
	v_mul_f32_e32 v250, v242, v250
	v_mul_f32_e32 v251, v243, v251
	v_mul_f32_e32 v248, v248, v244
	v_mul_f32_e32 v249, v249, v245
	v_mul_f32_e32 v250, v250, v246
	v_mul_f32_e32 v251, v251, v247
	v_cvt_pk_bf16_f32 v230, v248, v249
	v_cvt_pk_bf16_f32 v231, v250, v251
	s_add_u32 s56, s24, 0x0
	s_addc_u32 s57, s25, 0
	global_load_dwordx4 v[130:133], v253, s[56:57] offset:16
	s_add_u32 s56, s24, 0x2c00
	s_addc_u32 s57, s25, 0
	global_load_dwordx4 v[134:137], v253, s[56:57] offset:16
	s_add_u32 s56, s24, 0x5800
	s_addc_u32 s57, s25, 0
	global_load_dwordx4 v[138:141], v253, s[56:57] offset:16
	s_add_u32 s56, s24, 0x8400
	s_addc_u32 s57, s25, 0
	global_load_dwordx4 v[142:145], v253, s[56:57] offset:16
	s_add_u32 s56, s24, 0xb000
	s_addc_u32 s57, s25, 0
	global_load_dwordx4 v[146:149], v253, s[56:57] offset:16
	s_add_u32 s56, s24, 0xdc00
	s_addc_u32 s57, s25, 0
	global_load_dwordx4 v[150:153], v253, s[56:57] offset:16
	v_and_b32_e32 v240, 15, v194
	v_add_u32_e32 v240, 1, v240
	v_and_b32_e32 v240, 16, v240
	v_lshl_add_u32 v240, v240, 4, v205
	ds_read_b128 v[190:193], v240 offset:0
	ds_read_b128 v[208:211], v240 offset:128
	s_waitcnt lgkmcnt(0)
	v_mul_f32_e32 v240, v114, v94
	v_mul_f32_e32 v241, v115, v95
	v_mul_f32_e32 v242, v116, v96
	v_mul_f32_e32 v243, v117, v97
	v_fmac_f32_dpp v240, v94, v106 row_shr:1 row_mask:0xf bank_mask:0xf bound_ctrl:1
	v_fmac_f32_dpp v241, v95, v107 row_shr:1 row_mask:0xf bank_mask:0xf bound_ctrl:1
	v_fmac_f32_dpp v242, v96, v108 row_shr:1 row_mask:0xf bank_mask:0xf bound_ctrl:1
	v_fmac_f32_dpp v243, v97, v109 row_shr:1 row_mask:0xf bank_mask:0xf bound_ctrl:1
	v_fmac_f32_dpp v240, v94, v98 row_shr:2 row_mask:0xf bank_mask:0xf bound_ctrl:1
	v_fmac_f32_dpp v241, v95, v99 row_shr:2 row_mask:0xf bank_mask:0xf bound_ctrl:1
	v_fmac_f32_dpp v242, v96, v100 row_shr:2 row_mask:0xf bank_mask:0xf bound_ctrl:1
	v_fmac_f32_dpp v243, v97, v101 row_shr:2 row_mask:0xf bank_mask:0xf bound_ctrl:1
	v_fmac_f32_dpp v240, v190, v154 row_ror:1 row_mask:0xf bank_mask:0xf
	v_fmac_f32_dpp v241, v191, v155 row_ror:1 row_mask:0xf bank_mask:0xf
	v_fmac_f32_dpp v242, v192, v156 row_ror:1 row_mask:0xf bank_mask:0xf
	v_fmac_f32_dpp v243, v193, v157 row_ror:1 row_mask:0xf bank_mask:0xf
	v_fmac_f32_dpp v240, v190, v162 row_ror:2 row_mask:0xf bank_mask:0xf
	v_fmac_f32_dpp v241, v191, v163 row_ror:2 row_mask:0xf bank_mask:0xf
	v_fmac_f32_dpp v242, v192, v164 row_ror:2 row_mask:0xf bank_mask:0xf
	v_fmac_f32_dpp v243, v193, v165 row_ror:2 row_mask:0xf bank_mask:0xf
	v_mul_f32_e32 v244, v118, v90
	v_mul_f32_e32 v245, v119, v91
	v_mul_f32_e32 v246, v120, v92
	v_mul_f32_e32 v247, v121, v93
	v_fmac_f32_dpp v244, v90, v110 row_shr:1 row_mask:0xf bank_mask:0xf bound_ctrl:1
	v_fmac_f32_dpp v245, v91, v111 row_shr:1 row_mask:0xf bank_mask:0xf bound_ctrl:1
	v_fmac_f32_dpp v246, v92, v112 row_shr:1 row_mask:0xf bank_mask:0xf bound_ctrl:1
	v_fmac_f32_dpp v247, v93, v113 row_shr:1 row_mask:0xf bank_mask:0xf bound_ctrl:1
	v_fmac_f32_dpp v244, v90, v102 row_shr:2 row_mask:0xf bank_mask:0xf bound_ctrl:1
	v_fmac_f32_dpp v245, v91, v103 row_shr:2 row_mask:0xf bank_mask:0xf bound_ctrl:1
	v_fmac_f32_dpp v246, v92, v104 row_shr:2 row_mask:0xf bank_mask:0xf bound_ctrl:1
	v_fmac_f32_dpp v247, v93, v105 row_shr:2 row_mask:0xf bank_mask:0xf bound_ctrl:1
	v_fmac_f32_dpp v244, v208, v158 row_ror:1 row_mask:0xf bank_mask:0xf
	v_fmac_f32_dpp v245, v209, v159 row_ror:1 row_mask:0xf bank_mask:0xf
	v_fmac_f32_dpp v246, v210, v160 row_ror:1 row_mask:0xf bank_mask:0xf
	v_fmac_f32_dpp v247, v211, v161 row_ror:1 row_mask:0xf bank_mask:0xf
	v_fmac_f32_dpp v244, v208, v166 row_ror:2 row_mask:0xf bank_mask:0xf
	v_fmac_f32_dpp v245, v209, v167 row_ror:2 row_mask:0xf bank_mask:0xf
	v_fmac_f32_dpp v246, v210, v168 row_ror:2 row_mask:0xf bank_mask:0xf
	v_fmac_f32_dpp v247, v211, v169 row_ror:2 row_mask:0xf bank_mask:0xf
	v_mul_f32_e32 v248, 0xbfb8aa3b, v240
	v_mul_f32_e32 v249, 0xbfb8aa3b, v241
	v_mul_f32_e32 v250, 0xbfb8aa3b, v242
	v_mul_f32_e32 v251, 0xbfb8aa3b, v243
	v_exp_f32_e32 v248, v248
	v_exp_f32_e32 v249, v249
	v_exp_f32_e32 v250, v250
	v_exp_f32_e32 v251, v251
	v_add_f32_e32 v248, 1.0, v248
	v_add_f32_e32 v249, 1.0, v249
	v_add_f32_e32 v250, 1.0, v250
	v_add_f32_e32 v251, 1.0, v251
; __device__ __forceinline__ unsigned cvt_pk_bf16(float lo, float hi) { f32x2_t_ v = {lo, hi}; bf16x2_t_ b = __builtin_convertvector(v, bf16x2_t_); return __builtin_bit_cast(unsigned, b); }
; __device__ __forceinline__ float dpp_ror1(float v) { return __builtin_bit_cast(float, __builtin_amdgcn_update_dpp(0, __builtin_bit_cast(int, v), 0x121, 0xf, 0xf, false)); }
; __device__ __forceinline__ float dpp_ror2(float v) { return __builtin_bit_cast(float, __builtin_amdgcn_update_dpp(0, __builtin_bit_cast(int, v), 0x122, 0xf, 0xf, false)); }
;     __device__ __forceinline__ void operator()(const f32x4 (&acc)[2][2][4][2], const Unit& u, int wr, int wc, int fr, int fq) const {
;     ...
;                 for (int m = 0; m < 4; ++m) {
;                     float cv[2][4];
; #pragma unroll
;                     for (int bj = 0; bj < 2; ++bj)
; #pragma unroll
;                         for (int e = 0; e < 4; ++e) {
;                             const float x = acc[ai][bj][m][n][e];
;                             const float r1s = dpp_ror1(x), r2s = dpp_ror2(x);
;                             float r1p, r2p;
;                             if (m > 0) { const float xp = acc[ai][bj][m > 0 ? m - 1 : 0][n][e]; r1p = dpp_ror1(xp); r2p = dpp_ror2(xp); }
;                             else { r1p = h1[bj][e]; r2p = (fr == 0) ? h2[bj][e] : h1[bj][e]; }
;                             const float p1 = (fr == 0) ? r1p : r1s, p2 = (fr < 2) ? r2p : r2s;
;                             cv[bj][e] = wgt[0][bj][e] * p2 + wgt[1][bj][e] * p1 + wgt[2][bj][e] * x;
;                         }
;                     const int r = u.pm * BM + ai * HALF + wr * 64 + m * 16 + fr;
;                     if (top && m == 0 && fr < 2) {
; #pragma unroll
;                         for (int bj = 0; bj < 2; ++bj) *(f32x4*)(hb + fr * 256 + bj * 128 + 4 * n) = acc[0][bj][0][n];
;                     } else {
;                         float o[4];
; #pragma unroll
;                         for (int c = 0; c < 4; ++c) { const float g = cv[0][c]; o[c] = g * __builtin_amdgcn_rcpf(1.0f + __expf(-g)) * cv[1][c]; }
;                         u32x2 w; w.x = cvt_pk_bf16(o[0], o[1]); w.y = cvt_pk_bf16(o[2], o[3]);
;                         *(u32x2*)(act + (size_t)r * 2816 + colj + 4 * n) = w;
;                     }
	v_rcp_f32_e32 v248, v248
	v_rcp_f32_e32 v249, v249
	v_rcp_f32_e32 v250, v250
	v_rcp_f32_e32 v251, v251
	v_mul_f32_e32 v248, v240, v248
	v_mul_f32_e32 v249, v241, v249
	v_mul_f32_e32 v250, v242, v250
	v_mul_f32_e32 v251, v243, v251
	v_mul_f32_e32 v248, v248, v244
	v_mul_f32_e32 v249, v249, v245
	v_mul_f32_e32 v250, v250, v246
	v_mul_f32_e32 v251, v251, v247
	v_cvt_pk_bf16_f32 v232, v248, v249
	v_cvt_pk_bf16_f32 v233, v250, v251
	v_mul_f32_e32 v240, v114, v86
	v_mul_f32_e32 v241, v115, v87
	v_mul_f32_e32 v242, v116, v88
	v_mul_f32_e32 v243, v117, v89
	v_fmac_f32_dpp v240, v86, v106 row_shr:1 row_mask:0xf bank_mask:0xf bound_ctrl:1
	v_fmac_f32_dpp v241, v87, v107 row_shr:1 row_mask:0xf bank_mask:0xf bound_ctrl:1
	v_fmac_f32_dpp v242, v88, v108 row_shr:1 row_mask:0xf bank_mask:0xf bound_ctrl:1
	v_fmac_f32_dpp v243, v89, v109 row_shr:1 row_mask:0xf bank_mask:0xf bound_ctrl:1
	v_fmac_f32_dpp v240, v86, v98 row_shr:2 row_mask:0xf bank_mask:0xf bound_ctrl:1
	v_fmac_f32_dpp v241, v87, v99 row_shr:2 row_mask:0xf bank_mask:0xf bound_ctrl:1
	v_fmac_f32_dpp v242, v88, v100 row_shr:2 row_mask:0xf bank_mask:0xf bound_ctrl:1
	v_fmac_f32_dpp v243, v89, v101 row_shr:2 row_mask:0xf bank_mask:0xf bound_ctrl:1
	v_fmac_f32_dpp v240, v94, v154 row_ror:1 row_mask:0xf bank_mask:0xf
	v_fmac_f32_dpp v241, v95, v155 row_ror:1 row_mask:0xf bank_mask:0xf
	v_fmac_f32_dpp v242, v96, v156 row_ror:1 row_mask:0xf bank_mask:0xf
	v_fmac_f32_dpp v243, v97, v157 row_ror:1 row_mask:0xf bank_mask:0xf
	v_fmac_f32_dpp v240, v94, v162 row_ror:2 row_mask:0xf bank_mask:0xf
	v_fmac_f32_dpp v241, v95, v163 row_ror:2 row_mask:0xf bank_mask:0xf
	v_fmac_f32_dpp v242, v96, v164 row_ror:2 row_mask:0xf bank_mask:0xf
	v_fmac_f32_dpp v243, v97, v165 row_ror:2 row_mask:0xf bank_mask:0xf
	v_mul_f32_e32 v244, v118, v82
	v_mul_f32_e32 v245, v119, v83
	v_mul_f32_e32 v246, v120, v84
	v_mul_f32_e32 v247, v121, v85
	v_fmac_f32_dpp v244, v82, v110 row_shr:1 row_mask:0xf bank_mask:0xf bound_ctrl:1
	v_fmac_f32_dpp v245, v83, v111 row_shr:1 row_mask:0xf bank_mask:0xf bound_ctrl:1
	v_fmac_f32_dpp v246, v84, v112 row_shr:1 row_mask:0xf bank_mask:0xf bound_ctrl:1
	v_fmac_f32_dpp v247, v85, v113 row_shr:1 row_mask:0xf bank_mask:0xf bound_ctrl:1
	v_fmac_f32_dpp v244, v82, v102 row_shr:2 row_mask:0xf bank_mask:0xf bound_ctrl:1
	v_fmac_f32_dpp v245, v83, v103 row_shr:2 row_mask:0xf bank_mask:0xf bound_ctrl:1
	v_fmac_f32_dpp v246, v84, v104 row_shr:2 row_mask:0xf bank_mask:0xf bound_ctrl:1
	v_fmac_f32_dpp v247, v85, v105 row_shr:2 row_mask:0xf bank_mask:0xf bound_ctrl:1
	v_fmac_f32_dpp v244, v90, v158 row_ror:1 row_mask:0xf bank_mask:0xf
	v_fmac_f32_dpp v245, v91, v159 row_ror:1 row_mask:0xf bank_mask:0xf
	v_fmac_f32_dpp v246, v92, v160 row_ror:1 row_mask:0xf bank_mask:0xf
	v_fmac_f32_dpp v247, v93, v161 row_ror:1 row_mask:0xf bank_mask:0xf
	v_fmac_f32_dpp v244, v90, v166 row_ror:2 row_mask:0xf bank_mask:0xf
	v_fmac_f32_dpp v245, v91, v167 row_ror:2 row_mask:0xf bank_mask:0xf
	v_fmac_f32_dpp v246, v92, v168 row_ror:2 row_mask:0xf bank_mask:0xf
	v_fmac_f32_dpp v247, v93, v169 row_ror:2 row_mask:0xf bank_mask:0xf
	v_mul_f32_e32 v248, 0xbfb8aa3b, v240
	v_mul_f32_e32 v249, 0xbfb8aa3b, v241
	v_mul_f32_e32 v250, 0xbfb8aa3b, v242
	v_mul_f32_e32 v251, 0xbfb8aa3b, v243
	v_exp_f32_e32 v248, v248
	v_exp_f32_e32 v249, v249
	v_exp_f32_e32 v250, v250
	v_exp_f32_e32 v251, v251
	v_add_f32_e32 v248, 1.0, v248
	v_add_f32_e32 v249, 1.0, v249
	v_add_f32_e32 v250, 1.0, v250
	v_add_f32_e32 v251, 1.0, v251
	v_rcp_f32_e32 v248, v248
	v_rcp_f32_e32 v249, v249
	v_rcp_f32_e32 v250, v250
	v_rcp_f32_e32 v251, v251
	v_mul_f32_e32 v248, v240, v248
	v_mul_f32_e32 v249, v241, v249
	v_mul_f32_e32 v250, v242, v250
	v_mul_f32_e32 v251, v243, v251
	v_mul_f32_e32 v248, v248, v244
	v_mul_f32_e32 v249, v249, v245
	v_mul_f32_e32 v250, v250, v246
	v_mul_f32_e32 v251, v251, v247
	v_cvt_pk_bf16_f32 v234, v248, v249
	v_cvt_pk_bf16_f32 v235, v250, v251
	v_mul_f32_e32 v240, v114, v78
	v_mul_f32_e32 v241, v115, v79
	v_mul_f32_e32 v242, v116, v80
	v_mul_f32_e32 v243, v117, v81
	v_fmac_f32_dpp v240, v78, v106 row_shr:1 row_mask:0xf bank_mask:0xf bound_ctrl:1
	v_fmac_f32_dpp v241, v79, v107 row_shr:1 row_mask:0xf bank_mask:0xf bound_ctrl:1
	v_fmac_f32_dpp v242, v80, v108 row_shr:1 row_mask:0xf bank_mask:0xf bound_ctrl:1
	v_fmac_f32_dpp v243, v81, v109 row_shr:1 row_mask:0xf bank_mask:0xf bound_ctrl:1
	v_fmac_f32_dpp v240, v78, v98 row_shr:2 row_mask:0xf bank_mask:0xf bound_ctrl:1
	v_fmac_f32_dpp v241, v79, v99 row_shr:2 row_mask:0xf bank_mask:0xf bound_ctrl:1
	v_fmac_f32_dpp v242, v80, v100 row_shr:2 row_mask:0xf bank_mask:0xf bound_ctrl:1
	v_fmac_f32_dpp v243, v81, v101 row_shr:2 row_mask:0xf bank_mask:0xf bound_ctrl:1
	v_fmac_f32_dpp v240, v86, v154 row_ror:1 row_mask:0xf bank_mask:0xf
	v_fmac_f32_dpp v241, v87, v155 row_ror:1 row_mask:0xf bank_mask:0xf
	v_fmac_f32_dpp v242, v88, v156 row_ror:1 row_mask:0xf bank_mask:0xf
	v_fmac_f32_dpp v243, v89, v157 row_ror:1 row_mask:0xf bank_mask:0xf
	v_fmac_f32_dpp v240, v86, v162 row_ror:2 row_mask:0xf bank_mask:0xf
	v_fmac_f32_dpp v241, v87, v163 row_ror:2 row_mask:0xf bank_mask:0xf
	v_fmac_f32_dpp v242, v88, v164 row_ror:2 row_mask:0xf bank_mask:0xf
	v_fmac_f32_dpp v243, v89, v165 row_ror:2 row_mask:0xf bank_mask:0xf
	v_mul_f32_e32 v244, v118, v74
	v_mul_f32_e32 v245, v119, v75
	v_mul_f32_e32 v246, v120, v76
	v_mul_f32_e32 v247, v121, v77
	v_fmac_f32_dpp v244, v74, v110 row_shr:1 row_mask:0xf bank_mask:0xf bound_ctrl:1
	v_fmac_f32_dpp v245, v75, v111 row_shr:1 row_mask:0xf bank_mask:0xf bound_ctrl:1
	v_fmac_f32_dpp v246, v76, v112 row_shr:1 row_mask:0xf bank_mask:0xf bound_ctrl:1
; __device__ __forceinline__ unsigned cvt_pk_bf16(float lo, float hi) { f32x2_t_ v = {lo, hi}; bf16x2_t_ b = __builtin_convertvector(v, bf16x2_t_); return __builtin_bit_cast(unsigned, b); }
; __device__ __forceinline__ float dpp_ror1(float v) { return __builtin_bit_cast(float, __builtin_amdgcn_update_dpp(0, __builtin_bit_cast(int, v), 0x121, 0xf, 0xf, false)); }
; __device__ __forceinline__ float dpp_ror2(float v) { return __builtin_bit_cast(float, __builtin_amdgcn_update_dpp(0, __builtin_bit_cast(int, v), 0x122, 0xf, 0xf, false)); }
;     __device__ __forceinline__ void operator()(const f32x4 (&acc)[2][2][4][2], const Unit& u, int wr, int wc, int fr, int fq) const {
;     ...
;                 for (int m = 0; m < 4; ++m) {
;                     float cv[2][4];
; #pragma unroll
;                     for (int bj = 0; bj < 2; ++bj)
; #pragma unroll
;                         for (int e = 0; e < 4; ++e) {
;                             const float x = acc[ai][bj][m][n][e];
;                             const float r1s = dpp_ror1(x), r2s = dpp_ror2(x);
;                             float r1p, r2p;
;                             if (m > 0) { const float xp = acc[ai][bj][m > 0 ? m - 1 : 0][n][e]; r1p = dpp_ror1(xp); r2p = dpp_ror2(xp); }
;                             else { r1p = h1[bj][e]; r2p = (fr == 0) ? h2[bj][e] : h1[bj][e]; }
;                             const float p1 = (fr == 0) ? r1p : r1s, p2 = (fr < 2) ? r2p : r2s;
;                             cv[bj][e] = wgt[0][bj][e] * p2 + wgt[1][bj][e] * p1 + wgt[2][bj][e] * x;
;                         }
;                     const int r = u.pm * BM + ai * HALF + wr * 64 + m * 16 + fr;
;                     if (top && m == 0 && fr < 2) {
; #pragma unroll
;                         for (int bj = 0; bj < 2; ++bj) *(f32x4*)(hb + fr * 256 + bj * 128 + 4 * n) = acc[0][bj][0][n];
;                     } else {
;                         float o[4];
; #pragma unroll
;                         for (int c = 0; c < 4; ++c) { const float g = cv[0][c]; o[c] = g * __builtin_amdgcn_rcpf(1.0f + __expf(-g)) * cv[1][c]; }
;                         u32x2 w; w.x = cvt_pk_bf16(o[0], o[1]); w.y = cvt_pk_bf16(o[2], o[3]);
;                         *(u32x2*)(act + (size_t)r * 2816 + colj + 4 * n) = w;
;                     }
	v_fmac_f32_dpp v247, v77, v113 row_shr:1 row_mask:0xf bank_mask:0xf bound_ctrl:1
	v_fmac_f32_dpp v244, v74, v102 row_shr:2 row_mask:0xf bank_mask:0xf bound_ctrl:1
	v_fmac_f32_dpp v245, v75, v103 row_shr:2 row_mask:0xf bank_mask:0xf bound_ctrl:1
	v_fmac_f32_dpp v246, v76, v104 row_shr:2 row_mask:0xf bank_mask:0xf bound_ctrl:1
	v_fmac_f32_dpp v247, v77, v105 row_shr:2 row_mask:0xf bank_mask:0xf bound_ctrl:1
	v_fmac_f32_dpp v244, v82, v158 row_ror:1 row_mask:0xf bank_mask:0xf
	v_fmac_f32_dpp v245, v83, v159 row_ror:1 row_mask:0xf bank_mask:0xf
	v_fmac_f32_dpp v246, v84, v160 row_ror:1 row_mask:0xf bank_mask:0xf
	v_fmac_f32_dpp v247, v85, v161 row_ror:1 row_mask:0xf bank_mask:0xf
	v_fmac_f32_dpp v244, v82, v166 row_ror:2 row_mask:0xf bank_mask:0xf
	v_fmac_f32_dpp v245, v83, v167 row_ror:2 row_mask:0xf bank_mask:0xf
	v_fmac_f32_dpp v246, v84, v168 row_ror:2 row_mask:0xf bank_mask:0xf
	v_fmac_f32_dpp v247, v85, v169 row_ror:2 row_mask:0xf bank_mask:0xf
	v_mul_f32_e32 v248, 0xbfb8aa3b, v240
	v_mul_f32_e32 v249, 0xbfb8aa3b, v241
	v_mul_f32_e32 v250, 0xbfb8aa3b, v242
	v_mul_f32_e32 v251, 0xbfb8aa3b, v243
	v_exp_f32_e32 v248, v248
	v_exp_f32_e32 v249, v249
	v_exp_f32_e32 v250, v250
	v_exp_f32_e32 v251, v251
	v_add_f32_e32 v248, 1.0, v248
	v_add_f32_e32 v249, 1.0, v249
	v_add_f32_e32 v250, 1.0, v250
	v_add_f32_e32 v251, 1.0, v251
	v_rcp_f32_e32 v248, v248
	v_rcp_f32_e32 v249, v249
	v_rcp_f32_e32 v250, v250
	v_rcp_f32_e32 v251, v251
	v_mul_f32_e32 v248, v240, v248
	v_mul_f32_e32 v249, v241, v249
	v_mul_f32_e32 v250, v242, v250
	v_mul_f32_e32 v251, v243, v251
	v_mul_f32_e32 v248, v248, v244
	v_mul_f32_e32 v249, v249, v245
	v_mul_f32_e32 v250, v250, v246
	v_mul_f32_e32 v251, v251, v247
	v_cvt_pk_bf16_f32 v236, v248, v249
	v_cvt_pk_bf16_f32 v237, v250, v251
	v_mul_f32_e32 v240, v114, v14
	v_mul_f32_e32 v241, v115, v15
	v_mul_f32_e32 v242, v116, v16
	v_mul_f32_e32 v243, v117, v17
	v_fmac_f32_dpp v240, v14, v106 row_shr:1 row_mask:0xf bank_mask:0xf bound_ctrl:1
	v_fmac_f32_dpp v241, v15, v107 row_shr:1 row_mask:0xf bank_mask:0xf bound_ctrl:1
	v_fmac_f32_dpp v242, v16, v108 row_shr:1 row_mask:0xf bank_mask:0xf bound_ctrl:1
	v_fmac_f32_dpp v243, v17, v109 row_shr:1 row_mask:0xf bank_mask:0xf bound_ctrl:1
	v_fmac_f32_dpp v240, v14, v98 row_shr:2 row_mask:0xf bank_mask:0xf bound_ctrl:1
	v_fmac_f32_dpp v241, v15, v99 row_shr:2 row_mask:0xf bank_mask:0xf bound_ctrl:1
	v_fmac_f32_dpp v242, v16, v100 row_shr:2 row_mask:0xf bank_mask:0xf bound_ctrl:1
	v_fmac_f32_dpp v243, v17, v101 row_shr:2 row_mask:0xf bank_mask:0xf bound_ctrl:1
	v_fmac_f32_dpp v240, v78, v154 row_ror:1 row_mask:0xf bank_mask:0xf
	v_fmac_f32_dpp v241, v79, v155 row_ror:1 row_mask:0xf bank_mask:0xf
	v_fmac_f32_dpp v242, v80, v156 row_ror:1 row_mask:0xf bank_mask:0xf
	v_fmac_f32_dpp v243, v81, v157 row_ror:1 row_mask:0xf bank_mask:0xf
	v_fmac_f32_dpp v240, v78, v162 row_ror:2 row_mask:0xf bank_mask:0xf
	v_fmac_f32_dpp v241, v79, v163 row_ror:2 row_mask:0xf bank_mask:0xf
	v_fmac_f32_dpp v242, v80, v164 row_ror:2 row_mask:0xf bank_mask:0xf
	v_fmac_f32_dpp v243, v81, v165 row_ror:2 row_mask:0xf bank_mask:0xf
	v_mul_f32_e32 v244, v118, v6
	v_mul_f32_e32 v245, v119, v7
	v_mul_f32_e32 v246, v120, v8
	v_mul_f32_e32 v247, v121, v9
	v_fmac_f32_dpp v244, v6, v110 row_shr:1 row_mask:0xf bank_mask:0xf bound_ctrl:1
	v_fmac_f32_dpp v245, v7, v111 row_shr:1 row_mask:0xf bank_mask:0xf bound_ctrl:1
	v_fmac_f32_dpp v246, v8, v112 row_shr:1 row_mask:0xf bank_mask:0xf bound_ctrl:1
	v_fmac_f32_dpp v247, v9, v113 row_shr:1 row_mask:0xf bank_mask:0xf bound_ctrl:1
	v_fmac_f32_dpp v244, v6, v102 row_shr:2 row_mask:0xf bank_mask:0xf bound_ctrl:1
	v_fmac_f32_dpp v245, v7, v103 row_shr:2 row_mask:0xf bank_mask:0xf bound_ctrl:1
	v_fmac_f32_dpp v246, v8, v104 row_shr:2 row_mask:0xf bank_mask:0xf bound_ctrl:1
	v_fmac_f32_dpp v247, v9, v105 row_shr:2 row_mask:0xf bank_mask:0xf bound_ctrl:1
	v_fmac_f32_dpp v244, v74, v158 row_ror:1 row_mask:0xf bank_mask:0xf
	v_fmac_f32_dpp v245, v75, v159 row_ror:1 row_mask:0xf bank_mask:0xf
	v_fmac_f32_dpp v246, v76, v160 row_ror:1 row_mask:0xf bank_mask:0xf
	v_fmac_f32_dpp v247, v77, v161 row_ror:1 row_mask:0xf bank_mask:0xf
	v_fmac_f32_dpp v244, v74, v166 row_ror:2 row_mask:0xf bank_mask:0xf
	v_fmac_f32_dpp v245, v75, v167 row_ror:2 row_mask:0xf bank_mask:0xf
	v_fmac_f32_dpp v246, v76, v168 row_ror:2 row_mask:0xf bank_mask:0xf
	v_fmac_f32_dpp v247, v77, v169 row_ror:2 row_mask:0xf bank_mask:0xf
	v_mul_f32_e32 v248, 0xbfb8aa3b, v240
	v_mul_f32_e32 v249, 0xbfb8aa3b, v241
	v_mul_f32_e32 v250, 0xbfb8aa3b, v242
	v_mul_f32_e32 v251, 0xbfb8aa3b, v243
	v_exp_f32_e32 v248, v248
	v_exp_f32_e32 v249, v249
	v_exp_f32_e32 v250, v250
	v_exp_f32_e32 v251, v251
	v_add_f32_e32 v248, 1.0, v248
	v_add_f32_e32 v249, 1.0, v249
	v_add_f32_e32 v250, 1.0, v250
	v_add_f32_e32 v251, 1.0, v251
	v_rcp_f32_e32 v248, v248
	v_rcp_f32_e32 v249, v249
	v_rcp_f32_e32 v250, v250
	v_rcp_f32_e32 v251, v251
	v_mul_f32_e32 v248, v240, v248
	v_mul_f32_e32 v249, v241, v249
	v_mul_f32_e32 v250, v242, v250
	v_mul_f32_e32 v251, v243, v251
	v_mul_f32_e32 v248, v248, v244
	v_mul_f32_e32 v249, v249, v245
	v_mul_f32_e32 v250, v250, v246
	v_mul_f32_e32 v251, v251, v247
	v_cvt_pk_bf16_f32 v238, v248, v249
	v_cvt_pk_bf16_f32 v239, v250, v251
	s_waitcnt vmcnt(0)
	v_cndmask_b32_e64 v154, 0, v138, s[8:9]
	v_cndmask_b32_e64 v155, 0, v139, s[8:9]
	v_cndmask_b32_e64 v156, 0, v140, s[8:9]
	v_cndmask_b32_e64 v157, 0, v141, s[8:9]
	v_cndmask_b32_e64 v158, 0, v142, s[8:9]
	v_cndmask_b32_e64 v159, 0, v143, s[8:9]
	v_cndmask_b32_e64 v160, 0, v144, s[8:9]
	v_cndmask_b32_e64 v161, 0, v145, s[8:9]
	v_cndmask_b32_e64 v162, 0, v130, s[10:11]
	v_cndmask_b32_e64 v163, 0, v131, s[10:11]
	v_cndmask_b32_e64 v164, 0, v132, s[10:11]
	v_cndmask_b32_e64 v165, 0, v133, s[10:11]
	v_cndmask_b32_e64 v166, 0, v134, s[10:11]
	v_cndmask_b32_e64 v167, 0, v135, s[10:11]
	v_cndmask_b32_e64 v168, 0, v136, s[10:11]
	v_cndmask_b32_e64 v169, 0, v137, s[10:11]
	s_and_b64 vcc, exec, s[62:63]
	s_cbranch_vccz .Lup_n1a0_top
; __device__ __forceinline__ unsigned cvt_pk_bf16(float lo, float hi) { f32x2_t_ v = {lo, hi}; bf16x2_t_ b = __builtin_convertvector(v, bf16x2_t_); return __builtin_bit_cast(unsigned, b); }
; __device__ __forceinline__ float dpp_ror1(float v) { return __builtin_bit_cast(float, __builtin_amdgcn_update_dpp(0, __builtin_bit_cast(int, v), 0x121, 0xf, 0xf, false)); }
; __device__ __forceinline__ float dpp_ror2(float v) { return __builtin_bit_cast(float, __builtin_amdgcn_update_dpp(0, __builtin_bit_cast(int, v), 0x122, 0xf, 0xf, false)); }
;     __device__ __forceinline__ void operator()(const f32x4 (&acc)[2][2][4][2], const Unit& u, int wr, int wc, int fr, int fq) const {
;     ...
;                 for (int m = 0; m < 4; ++m) {
;                     float cv[2][4];
; #pragma unroll
;                     for (int bj = 0; bj < 2; ++bj)
; #pragma unroll
;                         for (int e = 0; e < 4; ++e) {
;                             const float x = acc[ai][bj][m][n][e];
;                             const float r1s = dpp_ror1(x), r2s = dpp_ror2(x);
;                             float r1p, r2p;
;                             if (m > 0) { const float xp = acc[ai][bj][m > 0 ? m - 1 : 0][n][e]; r1p = dpp_ror1(xp); r2p = dpp_ror2(xp); }
;                             else { r1p = h1[bj][e]; r2p = (fr == 0) ? h2[bj][e] : h1[bj][e]; }
;                             const float p1 = (fr == 0) ? r1p : r1s, p2 = (fr < 2) ? r2p : r2s;
;                             cv[bj][e] = wgt[0][bj][e] * p2 + wgt[1][bj][e] * p1 + wgt[2][bj][e] * x;
;                         }
;                     const int r = u.pm * BM + ai * HALF + wr * 64 + m * 16 + fr;
;                     if (top && m == 0 && fr < 2) {
; #pragma unroll
;                         for (int bj = 0; bj < 2; ++bj) *(f32x4*)(hb + fr * 256 + bj * 128 + 4 * n) = acc[0][bj][0][n];
;                     } else {
;                         float o[4];
; #pragma unroll
;                         for (int c = 0; c < 4; ++c) { const float g = cv[0][c]; o[c] = g * __builtin_amdgcn_rcpf(1.0f + __expf(-g)) * cv[1][c]; }
;                         u32x2 w; w.x = cvt_pk_bf16(o[0], o[1]); w.y = cvt_pk_bf16(o[2], o[3]);
;                         *(u32x2*)(act + (size_t)r * 2816 + colj + 4 * n) = w;
;                     }
	v_and_b32_e32 v240, 15, v194
	v_add_u32_e32 v240, 1, v240
	v_and_b32_e32 v240, 16, v240
	v_lshl_add_u32 v240, v240, 4, v204
	ds_read_b128 v[190:193], v240 offset:16
	ds_read_b128 v[208:211], v240 offset:144
	s_waitcnt lgkmcnt(0)
	v_mul_f32_e32 v240, v146, v70
	v_mul_f32_e32 v241, v147, v71
	v_mul_f32_e32 v242, v148, v72
	v_mul_f32_e32 v243, v149, v73
	v_fmac_f32_dpp v240, v70, v138 row_shr:1 row_mask:0xf bank_mask:0xf bound_ctrl:1
	v_fmac_f32_dpp v241, v71, v139 row_shr:1 row_mask:0xf bank_mask:0xf bound_ctrl:1
	v_fmac_f32_dpp v242, v72, v140 row_shr:1 row_mask:0xf bank_mask:0xf bound_ctrl:1
	v_fmac_f32_dpp v243, v73, v141 row_shr:1 row_mask:0xf bank_mask:0xf bound_ctrl:1
	v_fmac_f32_dpp v240, v70, v130 row_shr:2 row_mask:0xf bank_mask:0xf bound_ctrl:1
	v_fmac_f32_dpp v241, v71, v131 row_shr:2 row_mask:0xf bank_mask:0xf bound_ctrl:1
	v_fmac_f32_dpp v242, v72, v132 row_shr:2 row_mask:0xf bank_mask:0xf bound_ctrl:1
	v_fmac_f32_dpp v243, v73, v133 row_shr:2 row_mask:0xf bank_mask:0xf bound_ctrl:1
	v_fmac_f32_dpp v240, v190, v154 row_ror:1 row_mask:0xf bank_mask:0xf
	v_fmac_f32_dpp v241, v191, v155 row_ror:1 row_mask:0xf bank_mask:0xf
	v_fmac_f32_dpp v242, v192, v156 row_ror:1 row_mask:0xf bank_mask:0xf
	v_fmac_f32_dpp v243, v193, v157 row_ror:1 row_mask:0xf bank_mask:0xf
	v_fmac_f32_dpp v240, v190, v162 row_ror:2 row_mask:0xf bank_mask:0xf
	v_fmac_f32_dpp v241, v191, v163 row_ror:2 row_mask:0xf bank_mask:0xf
	v_fmac_f32_dpp v242, v192, v164 row_ror:2 row_mask:0xf bank_mask:0xf
	v_fmac_f32_dpp v243, v193, v165 row_ror:2 row_mask:0xf bank_mask:0xf
	v_mul_f32_e32 v244, v150, v66
	v_mul_f32_e32 v245, v151, v67
	v_mul_f32_e32 v246, v152, v68
	v_mul_f32_e32 v247, v153, v69
	v_fmac_f32_dpp v244, v66, v142 row_shr:1 row_mask:0xf bank_mask:0xf bound_ctrl:1
	v_fmac_f32_dpp v245, v67, v143 row_shr:1 row_mask:0xf bank_mask:0xf bound_ctrl:1
	v_fmac_f32_dpp v246, v68, v144 row_shr:1 row_mask:0xf bank_mask:0xf bound_ctrl:1
	v_fmac_f32_dpp v247, v69, v145 row_shr:1 row_mask:0xf bank_mask:0xf bound_ctrl:1
	v_fmac_f32_dpp v244, v66, v134 row_shr:2 row_mask:0xf bank_mask:0xf bound_ctrl:1
	v_fmac_f32_dpp v245, v67, v135 row_shr:2 row_mask:0xf bank_mask:0xf bound_ctrl:1
	v_fmac_f32_dpp v246, v68, v136 row_shr:2 row_mask:0xf bank_mask:0xf bound_ctrl:1
	v_fmac_f32_dpp v247, v69, v137 row_shr:2 row_mask:0xf bank_mask:0xf bound_ctrl:1
	v_fmac_f32_dpp v244, v208, v158 row_ror:1 row_mask:0xf bank_mask:0xf
	v_fmac_f32_dpp v245, v209, v159 row_ror:1 row_mask:0xf bank_mask:0xf
	v_fmac_f32_dpp v246, v210, v160 row_ror:1 row_mask:0xf bank_mask:0xf
	v_fmac_f32_dpp v247, v211, v161 row_ror:1 row_mask:0xf bank_mask:0xf
	v_fmac_f32_dpp v244, v208, v166 row_ror:2 row_mask:0xf bank_mask:0xf
	v_fmac_f32_dpp v245, v209, v167 row_ror:2 row_mask:0xf bank_mask:0xf
	v_fmac_f32_dpp v246, v210, v168 row_ror:2 row_mask:0xf bank_mask:0xf
	v_fmac_f32_dpp v247, v211, v169 row_ror:2 row_mask:0xf bank_mask:0xf
	v_mul_f32_e32 v248, 0xbfb8aa3b, v240
	v_mul_f32_e32 v249, 0xbfb8aa3b, v241
	v_mul_f32_e32 v250, 0xbfb8aa3b, v242
	v_mul_f32_e32 v251, 0xbfb8aa3b, v243
	v_exp_f32_e32 v248, v248
	v_exp_f32_e32 v249, v249
	v_exp_f32_e32 v250, v250
	v_exp_f32_e32 v251, v251
	v_add_f32_e32 v248, 1.0, v248
	v_add_f32_e32 v249, 1.0, v249
	v_add_f32_e32 v250, 1.0, v250
	v_add_f32_e32 v251, 1.0, v251
	v_rcp_f32_e32 v248, v248
	v_rcp_f32_e32 v249, v249
	v_rcp_f32_e32 v250, v250
	v_rcp_f32_e32 v251, v251
	v_mul_f32_e32 v248, v240, v248
	v_mul_f32_e32 v249, v241, v249
	v_mul_f32_e32 v250, v242, v250
	v_mul_f32_e32 v251, v243, v251
	v_mul_f32_e32 v248, v248, v244
	v_mul_f32_e32 v249, v249, v245
	v_mul_f32_e32 v250, v250, v246
	v_mul_f32_e32 v251, v251, v247
	s_branch .Lup_n1a0_join
.Lup_n1a0_top:
	v_mul_f32_e32 v240, v146, v70
	v_mul_f32_e32 v241, v147, v71
	v_mul_f32_e32 v242, v148, v72
	v_mul_f32_e32 v243, v149, v73
	v_fmac_f32_dpp v240, v70, v138 row_shr:1 row_mask:0xf bank_mask:0xf bound_ctrl:1
	v_fmac_f32_dpp v241, v71, v139 row_shr:1 row_mask:0xf bank_mask:0xf bound_ctrl:1
	v_fmac_f32_dpp v242, v72, v140 row_shr:1 row_mask:0xf bank_mask:0xf bound_ctrl:1
	v_fmac_f32_dpp v243, v73, v141 row_shr:1 row_mask:0xf bank_mask:0xf bound_ctrl:1
	v_fmac_f32_dpp v240, v70, v130 row_shr:2 row_mask:0xf bank_mask:0xf bound_ctrl:1
	v_fmac_f32_dpp v241, v71, v131 row_shr:2 row_mask:0xf bank_mask:0xf bound_ctrl:1
	v_fmac_f32_dpp v242, v72, v132 row_shr:2 row_mask:0xf bank_mask:0xf bound_ctrl:1
	v_fmac_f32_dpp v243, v73, v133 row_shr:2 row_mask:0xf bank_mask:0xf bound_ctrl:1
	v_mul_f32_e32 v244, v150, v66
	v_mul_f32_e32 v245, v151, v67
	v_mul_f32_e32 v246, v152, v68
	v_mul_f32_e32 v247, v153, v69
	v_fmac_f32_dpp v244, v66, v142 row_shr:1 row_mask:0xf bank_mask:0xf bound_ctrl:1
	v_fmac_f32_dpp v245, v67, v143 row_shr:1 row_mask:0xf bank_mask:0xf bound_ctrl:1
	v_fmac_f32_dpp v246, v68, v144 row_shr:1 row_mask:0xf bank_mask:0xf bound_ctrl:1
	v_fmac_f32_dpp v247, v69, v145 row_shr:1 row_mask:0xf bank_mask:0xf bound_ctrl:1
	v_fmac_f32_dpp v244, v66, v134 row_shr:2 row_mask:0xf bank_mask:0xf bound_ctrl:1
	v_fmac_f32_dpp v245, v67, v135 row_shr:2 row_mask:0xf bank_mask:0xf bound_ctrl:1
	v_fmac_f32_dpp v246, v68, v136 row_shr:2 row_mask:0xf bank_mask:0xf bound_ctrl:1
	v_fmac_f32_dpp v247, v69, v137 row_shr:2 row_mask:0xf bank_mask:0xf bound_ctrl:1
	v_mul_f32_e32 v248, 0xbfb8aa3b, v240
	v_mul_f32_e32 v249, 0xbfb8aa3b, v241
	v_mul_f32_e32 v250, 0xbfb8aa3b, v242
	v_mul_f32_e32 v251, 0xbfb8aa3b, v243
	v_exp_f32_e32 v248, v248
	v_exp_f32_e32 v249, v249
	v_exp_f32_e32 v250, v250
	v_exp_f32_e32 v251, v251
	v_add_f32_e32 v248, 1.0, v248
	v_add_f32_e32 v249, 1.0, v249
	v_add_f32_e32 v250, 1.0, v250
	v_add_f32_e32 v251, 1.0, v251
	v_rcp_f32_e32 v248, v248
	v_rcp_f32_e32 v249, v249
	v_rcp_f32_e32 v250, v250
	v_rcp_f32_e32 v251, v251
	v_mul_f32_e32 v248, v240, v248
	v_mul_f32_e32 v249, v241, v249
	v_mul_f32_e32 v250, v242, v250
	v_mul_f32_e32 v251, v243, v251
	v_mul_f32_e32 v248, v248, v244
	v_mul_f32_e32 v249, v249, v245
	v_mul_f32_e32 v250, v250, v246
	v_mul_f32_e32 v251, v251, v247
; __device__ __forceinline__ unsigned cvt_pk_bf16(float lo, float hi) { f32x2_t_ v = {lo, hi}; bf16x2_t_ b = __builtin_convertvector(v, bf16x2_t_); return __builtin_bit_cast(unsigned, b); }
; __device__ __forceinline__ float dpp_ror1(float v) { return __builtin_bit_cast(float, __builtin_amdgcn_update_dpp(0, __builtin_bit_cast(int, v), 0x121, 0xf, 0xf, false)); }
; __device__ __forceinline__ float dpp_ror2(float v) { return __builtin_bit_cast(float, __builtin_amdgcn_update_dpp(0, __builtin_bit_cast(int, v), 0x122, 0xf, 0xf, false)); }
;     __device__ __forceinline__ void operator()(const f32x4 (&acc)[2][2][4][2], const Unit& u, int wr, int wc, int fr, int fq) const {
;     ...
;                 for (int m = 0; m < 4; ++m) {
;                     float cv[2][4];
; #pragma unroll
;                     for (int bj = 0; bj < 2; ++bj)
; #pragma unroll
;                         for (int e = 0; e < 4; ++e) {
;                             const float x = acc[ai][bj][m][n][e];
;                             const float r1s = dpp_ror1(x), r2s = dpp_ror2(x);
;                             float r1p, r2p;
;                             if (m > 0) { const float xp = acc[ai][bj][m > 0 ? m - 1 : 0][n][e]; r1p = dpp_ror1(xp); r2p = dpp_ror2(xp); }
;                             else { r1p = h1[bj][e]; r2p = (fr == 0) ? h2[bj][e] : h1[bj][e]; }
;                             const float p1 = (fr == 0) ? r1p : r1s, p2 = (fr < 2) ? r2p : r2s;
;                             cv[bj][e] = wgt[0][bj][e] * p2 + wgt[1][bj][e] * p1 + wgt[2][bj][e] * x;
;                         }
;                     const int r = u.pm * BM + ai * HALF + wr * 64 + m * 16 + fr;
;                     if (top && m == 0 && fr < 2) {
; #pragma unroll
;                         for (int bj = 0; bj < 2; ++bj) *(f32x4*)(hb + fr * 256 + bj * 128 + 4 * n) = acc[0][bj][0][n];
;                     } else {
;                         float o[4];
; #pragma unroll
;                         for (int c = 0; c < 4; ++c) { const float g = cv[0][c]; o[c] = g * __builtin_amdgcn_rcpf(1.0f + __expf(-g)) * cv[1][c]; }
;                         u32x2 w; w.x = cvt_pk_bf16(o[0], o[1]); w.y = cvt_pk_bf16(o[2], o[3]);
;                         *(u32x2*)(act + (size_t)r * 2816 + colj + 4 * n) = w;
;                     }
.Lup_n1a0_join:
	v_cvt_pk_bf16_f32 v100, v248, v249
	v_cvt_pk_bf16_f32 v101, v250, v251
	v_mov_b32_e32 v98, v224
	v_mov_b32_e32 v99, v225
	s_add_u32 s58, s30, 0x0
	s_addc_u32 s59, s31, 0
	s_and_b64 vcc, exec, s[62:63]
	s_cbranch_vccnz .Lup_st00
	s_andn2_b64 exec, exec, s[10:11]
.Lup_st00:
	global_store_dwordx4 v252, v[98:101], s[58:59]
	s_mov_b64 exec, -1
	s_nop 1
	v_mul_f32_e32 v240, v146, v62
	v_mul_f32_e32 v241, v147, v63
	v_mul_f32_e32 v242, v148, v64
	v_mul_f32_e32 v243, v149, v65
	v_fmac_f32_dpp v240, v62, v138 row_shr:1 row_mask:0xf bank_mask:0xf bound_ctrl:1
	v_fmac_f32_dpp v241, v63, v139 row_shr:1 row_mask:0xf bank_mask:0xf bound_ctrl:1
	v_fmac_f32_dpp v242, v64, v140 row_shr:1 row_mask:0xf bank_mask:0xf bound_ctrl:1
	v_fmac_f32_dpp v243, v65, v141 row_shr:1 row_mask:0xf bank_mask:0xf bound_ctrl:1
	v_fmac_f32_dpp v240, v62, v130 row_shr:2 row_mask:0xf bank_mask:0xf bound_ctrl:1
	v_fmac_f32_dpp v241, v63, v131 row_shr:2 row_mask:0xf bank_mask:0xf bound_ctrl:1
	v_fmac_f32_dpp v242, v64, v132 row_shr:2 row_mask:0xf bank_mask:0xf bound_ctrl:1
	v_fmac_f32_dpp v243, v65, v133 row_shr:2 row_mask:0xf bank_mask:0xf bound_ctrl:1
	v_fmac_f32_dpp v240, v70, v154 row_ror:1 row_mask:0xf bank_mask:0xf
	v_fmac_f32_dpp v241, v71, v155 row_ror:1 row_mask:0xf bank_mask:0xf
	v_fmac_f32_dpp v242, v72, v156 row_ror:1 row_mask:0xf bank_mask:0xf
	v_fmac_f32_dpp v243, v73, v157 row_ror:1 row_mask:0xf bank_mask:0xf
	v_fmac_f32_dpp v240, v70, v162 row_ror:2 row_mask:0xf bank_mask:0xf
	v_fmac_f32_dpp v241, v71, v163 row_ror:2 row_mask:0xf bank_mask:0xf
	v_fmac_f32_dpp v242, v72, v164 row_ror:2 row_mask:0xf bank_mask:0xf
	v_fmac_f32_dpp v243, v73, v165 row_ror:2 row_mask:0xf bank_mask:0xf
	v_mul_f32_e32 v244, v150, v58
	v_mul_f32_e32 v245, v151, v59
	v_mul_f32_e32 v246, v152, v60
	v_mul_f32_e32 v247, v153, v61
	v_fmac_f32_dpp v244, v58, v142 row_shr:1 row_mask:0xf bank_mask:0xf bound_ctrl:1
	v_fmac_f32_dpp v245, v59, v143 row_shr:1 row_mask:0xf bank_mask:0xf bound_ctrl:1
	v_fmac_f32_dpp v246, v60, v144 row_shr:1 row_mask:0xf bank_mask:0xf bound_ctrl:1
	v_fmac_f32_dpp v247, v61, v145 row_shr:1 row_mask:0xf bank_mask:0xf bound_ctrl:1
	v_fmac_f32_dpp v244, v58, v134 row_shr:2 row_mask:0xf bank_mask:0xf bound_ctrl:1
	v_fmac_f32_dpp v245, v59, v135 row_shr:2 row_mask:0xf bank_mask:0xf bound_ctrl:1
	v_fmac_f32_dpp v246, v60, v136 row_shr:2 row_mask:0xf bank_mask:0xf bound_ctrl:1
	v_fmac_f32_dpp v247, v61, v137 row_shr:2 row_mask:0xf bank_mask:0xf bound_ctrl:1
	v_fmac_f32_dpp v244, v66, v158 row_ror:1 row_mask:0xf bank_mask:0xf
	v_fmac_f32_dpp v245, v67, v159 row_ror:1 row_mask:0xf bank_mask:0xf
	v_fmac_f32_dpp v246, v68, v160 row_ror:1 row_mask:0xf bank_mask:0xf
	v_fmac_f32_dpp v247, v69, v161 row_ror:1 row_mask:0xf bank_mask:0xf
	v_fmac_f32_dpp v244, v66, v166 row_ror:2 row_mask:0xf bank_mask:0xf
	v_fmac_f32_dpp v245, v67, v167 row_ror:2 row_mask:0xf bank_mask:0xf
	v_fmac_f32_dpp v246, v68, v168 row_ror:2 row_mask:0xf bank_mask:0xf
	v_fmac_f32_dpp v247, v69, v169 row_ror:2 row_mask:0xf bank_mask:0xf
	v_mul_f32_e32 v248, 0xbfb8aa3b, v240
	v_mul_f32_e32 v249, 0xbfb8aa3b, v241
	v_mul_f32_e32 v250, 0xbfb8aa3b, v242
	v_mul_f32_e32 v251, 0xbfb8aa3b, v243
	v_exp_f32_e32 v248, v248
	v_exp_f32_e32 v249, v249
	v_exp_f32_e32 v250, v250
	v_exp_f32_e32 v251, v251
	v_add_f32_e32 v248, 1.0, v248
	v_add_f32_e32 v249, 1.0, v249
	v_add_f32_e32 v250, 1.0, v250
	v_add_f32_e32 v251, 1.0, v251
	v_rcp_f32_e32 v248, v248
	v_rcp_f32_e32 v249, v249
	v_rcp_f32_e32 v250, v250
	v_rcp_f32_e32 v251, v251
	v_mul_f32_e32 v248, v240, v248
	v_mul_f32_e32 v249, v241, v249
	v_mul_f32_e32 v250, v242, v250
	v_mul_f32_e32 v251, v243, v251
	v_mul_f32_e32 v248, v248, v244
	v_mul_f32_e32 v249, v249, v245
	v_mul_f32_e32 v250, v250, v246
	v_mul_f32_e32 v251, v251, v247
	v_cvt_pk_bf16_f32 v104, v248, v249
	v_cvt_pk_bf16_f32 v105, v250, v251
	v_mov_b32_e32 v102, v226
	v_mov_b32_e32 v103, v227
	s_add_u32 s58, s30, 0x16000
	s_addc_u32 s59, s31, 0
	global_store_dwordx4 v252, v[102:105], s[58:59]
	v_mul_f32_e32 v240, v146, v54
	v_mul_f32_e32 v241, v147, v55
	v_mul_f32_e32 v242, v148, v56
	v_mul_f32_e32 v243, v149, v57
	v_fmac_f32_dpp v240, v54, v138 row_shr:1 row_mask:0xf bank_mask:0xf bound_ctrl:1
	v_fmac_f32_dpp v241, v55, v139 row_shr:1 row_mask:0xf bank_mask:0xf bound_ctrl:1
	v_fmac_f32_dpp v242, v56, v140 row_shr:1 row_mask:0xf bank_mask:0xf bound_ctrl:1
	v_fmac_f32_dpp v243, v57, v141 row_shr:1 row_mask:0xf bank_mask:0xf bound_ctrl:1
	v_fmac_f32_dpp v240, v54, v130 row_shr:2 row_mask:0xf bank_mask:0xf bound_ctrl:1
	v_fmac_f32_dpp v241, v55, v131 row_shr:2 row_mask:0xf bank_mask:0xf bound_ctrl:1
	v_fmac_f32_dpp v242, v56, v132 row_shr:2 row_mask:0xf bank_mask:0xf bound_ctrl:1
	v_fmac_f32_dpp v243, v57, v133 row_shr:2 row_mask:0xf bank_mask:0xf bound_ctrl:1
	v_fmac_f32_dpp v240, v62, v154 row_ror:1 row_mask:0xf bank_mask:0xf
	v_fmac_f32_dpp v241, v63, v155 row_ror:1 row_mask:0xf bank_mask:0xf
	v_fmac_f32_dpp v242, v64, v156 row_ror:1 row_mask:0xf bank_mask:0xf
	v_fmac_f32_dpp v243, v65, v157 row_ror:1 row_mask:0xf bank_mask:0xf
	v_fmac_f32_dpp v240, v62, v162 row_ror:2 row_mask:0xf bank_mask:0xf
	v_fmac_f32_dpp v241, v63, v163 row_ror:2 row_mask:0xf bank_mask:0xf
	v_fmac_f32_dpp v242, v64, v164 row_ror:2 row_mask:0xf bank_mask:0xf
	v_fmac_f32_dpp v243, v65, v165 row_ror:2 row_mask:0xf bank_mask:0xf
	v_mul_f32_e32 v244, v150, v50
	v_mul_f32_e32 v245, v151, v51
	v_mul_f32_e32 v246, v152, v52
	v_mul_f32_e32 v247, v153, v53
	v_fmac_f32_dpp v244, v50, v142 row_shr:1 row_mask:0xf bank_mask:0xf bound_ctrl:1
	v_fmac_f32_dpp v245, v51, v143 row_shr:1 row_mask:0xf bank_mask:0xf bound_ctrl:1
; __device__ __forceinline__ unsigned cvt_pk_bf16(float lo, float hi) { f32x2_t_ v = {lo, hi}; bf16x2_t_ b = __builtin_convertvector(v, bf16x2_t_); return __builtin_bit_cast(unsigned, b); }
; __device__ __forceinline__ float dpp_ror1(float v) { return __builtin_bit_cast(float, __builtin_amdgcn_update_dpp(0, __builtin_bit_cast(int, v), 0x121, 0xf, 0xf, false)); }
; __device__ __forceinline__ float dpp_ror2(float v) { return __builtin_bit_cast(float, __builtin_amdgcn_update_dpp(0, __builtin_bit_cast(int, v), 0x122, 0xf, 0xf, false)); }
;     __device__ __forceinline__ void operator()(const f32x4 (&acc)[2][2][4][2], const Unit& u, int wr, int wc, int fr, int fq) const {
;     ...
;                 for (int m = 0; m < 4; ++m) {
;                     float cv[2][4];
; #pragma unroll
;                     for (int bj = 0; bj < 2; ++bj)
; #pragma unroll
;                         for (int e = 0; e < 4; ++e) {
;                             const float x = acc[ai][bj][m][n][e];
;                             const float r1s = dpp_ror1(x), r2s = dpp_ror2(x);
;                             float r1p, r2p;
;                             if (m > 0) { const float xp = acc[ai][bj][m > 0 ? m - 1 : 0][n][e]; r1p = dpp_ror1(xp); r2p = dpp_ror2(xp); }
;                             else { r1p = h1[bj][e]; r2p = (fr == 0) ? h2[bj][e] : h1[bj][e]; }
;                             const float p1 = (fr == 0) ? r1p : r1s, p2 = (fr < 2) ? r2p : r2s;
;                             cv[bj][e] = wgt[0][bj][e] * p2 + wgt[1][bj][e] * p1 + wgt[2][bj][e] * x;
;                         }
;                     const int r = u.pm * BM + ai * HALF + wr * 64 + m * 16 + fr;
;                     if (top && m == 0 && fr < 2) {
; #pragma unroll
;                         for (int bj = 0; bj < 2; ++bj) *(f32x4*)(hb + fr * 256 + bj * 128 + 4 * n) = acc[0][bj][0][n];
;                     } else {
;                         float o[4];
; #pragma unroll
;                         for (int c = 0; c < 4; ++c) { const float g = cv[0][c]; o[c] = g * __builtin_amdgcn_rcpf(1.0f + __expf(-g)) * cv[1][c]; }
;                         u32x2 w; w.x = cvt_pk_bf16(o[0], o[1]); w.y = cvt_pk_bf16(o[2], o[3]);
;                         *(u32x2*)(act + (size_t)r * 2816 + colj + 4 * n) = w;
;                     }
	v_fmac_f32_dpp v246, v52, v144 row_shr:1 row_mask:0xf bank_mask:0xf bound_ctrl:1
	v_fmac_f32_dpp v247, v53, v145 row_shr:1 row_mask:0xf bank_mask:0xf bound_ctrl:1
	v_fmac_f32_dpp v244, v50, v134 row_shr:2 row_mask:0xf bank_mask:0xf bound_ctrl:1
	v_fmac_f32_dpp v245, v51, v135 row_shr:2 row_mask:0xf bank_mask:0xf bound_ctrl:1
	v_fmac_f32_dpp v246, v52, v136 row_shr:2 row_mask:0xf bank_mask:0xf bound_ctrl:1
	v_fmac_f32_dpp v247, v53, v137 row_shr:2 row_mask:0xf bank_mask:0xf bound_ctrl:1
	v_fmac_f32_dpp v244, v58, v158 row_ror:1 row_mask:0xf bank_mask:0xf
	v_fmac_f32_dpp v245, v59, v159 row_ror:1 row_mask:0xf bank_mask:0xf
	v_fmac_f32_dpp v246, v60, v160 row_ror:1 row_mask:0xf bank_mask:0xf
	v_fmac_f32_dpp v247, v61, v161 row_ror:1 row_mask:0xf bank_mask:0xf
	v_fmac_f32_dpp v244, v58, v166 row_ror:2 row_mask:0xf bank_mask:0xf
	v_fmac_f32_dpp v245, v59, v167 row_ror:2 row_mask:0xf bank_mask:0xf
	v_fmac_f32_dpp v246, v60, v168 row_ror:2 row_mask:0xf bank_mask:0xf
	v_fmac_f32_dpp v247, v61, v169 row_ror:2 row_mask:0xf bank_mask:0xf
	v_mul_f32_e32 v248, 0xbfb8aa3b, v240
	v_mul_f32_e32 v249, 0xbfb8aa3b, v241
	v_mul_f32_e32 v250, 0xbfb8aa3b, v242
	v_mul_f32_e32 v251, 0xbfb8aa3b, v243
	v_exp_f32_e32 v248, v248
	v_exp_f32_e32 v249, v249
	v_exp_f32_e32 v250, v250
	v_exp_f32_e32 v251, v251
	v_add_f32_e32 v248, 1.0, v248
	v_add_f32_e32 v249, 1.0, v249
	v_add_f32_e32 v250, 1.0, v250
	v_add_f32_e32 v251, 1.0, v251
	v_rcp_f32_e32 v248, v248
	v_rcp_f32_e32 v249, v249
	v_rcp_f32_e32 v250, v250
	v_rcp_f32_e32 v251, v251
	v_mul_f32_e32 v248, v240, v248
	v_mul_f32_e32 v249, v241, v249
	v_mul_f32_e32 v250, v242, v250
	v_mul_f32_e32 v251, v243, v251
	v_mul_f32_e32 v248, v248, v244
	v_mul_f32_e32 v249, v249, v245
	v_mul_f32_e32 v250, v250, v246
	v_mul_f32_e32 v251, v251, v247
	v_cvt_pk_bf16_f32 v108, v248, v249
	v_cvt_pk_bf16_f32 v109, v250, v251
	v_mov_b32_e32 v106, v228
	v_mov_b32_e32 v107, v229
	s_add_u32 s58, s30, 0x2c000
	s_addc_u32 s59, s31, 0
	global_store_dwordx4 v252, v[106:109], s[58:59]
	v_mul_f32_e32 v240, v146, v46
	v_mul_f32_e32 v241, v147, v47
	v_mul_f32_e32 v242, v148, v48
	v_mul_f32_e32 v243, v149, v49
	v_fmac_f32_dpp v240, v46, v138 row_shr:1 row_mask:0xf bank_mask:0xf bound_ctrl:1
	v_fmac_f32_dpp v241, v47, v139 row_shr:1 row_mask:0xf bank_mask:0xf bound_ctrl:1
	v_fmac_f32_dpp v242, v48, v140 row_shr:1 row_mask:0xf bank_mask:0xf bound_ctrl:1
	v_fmac_f32_dpp v243, v49, v141 row_shr:1 row_mask:0xf bank_mask:0xf bound_ctrl:1
	v_fmac_f32_dpp v240, v46, v130 row_shr:2 row_mask:0xf bank_mask:0xf bound_ctrl:1
	v_fmac_f32_dpp v241, v47, v131 row_shr:2 row_mask:0xf bank_mask:0xf bound_ctrl:1
	v_fmac_f32_dpp v242, v48, v132 row_shr:2 row_mask:0xf bank_mask:0xf bound_ctrl:1
	v_fmac_f32_dpp v243, v49, v133 row_shr:2 row_mask:0xf bank_mask:0xf bound_ctrl:1
	v_fmac_f32_dpp v240, v54, v154 row_ror:1 row_mask:0xf bank_mask:0xf
	v_fmac_f32_dpp v241, v55, v155 row_ror:1 row_mask:0xf bank_mask:0xf
	v_fmac_f32_dpp v242, v56, v156 row_ror:1 row_mask:0xf bank_mask:0xf
	v_fmac_f32_dpp v243, v57, v157 row_ror:1 row_mask:0xf bank_mask:0xf
	v_fmac_f32_dpp v240, v54, v162 row_ror:2 row_mask:0xf bank_mask:0xf
	v_fmac_f32_dpp v241, v55, v163 row_ror:2 row_mask:0xf bank_mask:0xf
	v_fmac_f32_dpp v242, v56, v164 row_ror:2 row_mask:0xf bank_mask:0xf
	v_fmac_f32_dpp v243, v57, v165 row_ror:2 row_mask:0xf bank_mask:0xf
	v_mul_f32_e32 v244, v150, v42
	v_mul_f32_e32 v245, v151, v43
	v_mul_f32_e32 v246, v152, v44
	v_mul_f32_e32 v247, v153, v45
	v_fmac_f32_dpp v244, v42, v142 row_shr:1 row_mask:0xf bank_mask:0xf bound_ctrl:1
	v_fmac_f32_dpp v245, v43, v143 row_shr:1 row_mask:0xf bank_mask:0xf bound_ctrl:1
	v_fmac_f32_dpp v246, v44, v144 row_shr:1 row_mask:0xf bank_mask:0xf bound_ctrl:1
	v_fmac_f32_dpp v247, v45, v145 row_shr:1 row_mask:0xf bank_mask:0xf bound_ctrl:1
	v_fmac_f32_dpp v244, v42, v134 row_shr:2 row_mask:0xf bank_mask:0xf bound_ctrl:1
	v_fmac_f32_dpp v245, v43, v135 row_shr:2 row_mask:0xf bank_mask:0xf bound_ctrl:1
	v_fmac_f32_dpp v246, v44, v136 row_shr:2 row_mask:0xf bank_mask:0xf bound_ctrl:1
	v_fmac_f32_dpp v247, v45, v137 row_shr:2 row_mask:0xf bank_mask:0xf bound_ctrl:1
	v_fmac_f32_dpp v244, v50, v158 row_ror:1 row_mask:0xf bank_mask:0xf
	v_fmac_f32_dpp v245, v51, v159 row_ror:1 row_mask:0xf bank_mask:0xf
	v_fmac_f32_dpp v246, v52, v160 row_ror:1 row_mask:0xf bank_mask:0xf
	v_fmac_f32_dpp v247, v53, v161 row_ror:1 row_mask:0xf bank_mask:0xf
	v_fmac_f32_dpp v244, v50, v166 row_ror:2 row_mask:0xf bank_mask:0xf
	v_fmac_f32_dpp v245, v51, v167 row_ror:2 row_mask:0xf bank_mask:0xf
	v_fmac_f32_dpp v246, v52, v168 row_ror:2 row_mask:0xf bank_mask:0xf
	v_fmac_f32_dpp v247, v53, v169 row_ror:2 row_mask:0xf bank_mask:0xf
	v_mul_f32_e32 v248, 0xbfb8aa3b, v240
	v_mul_f32_e32 v249, 0xbfb8aa3b, v241
	v_mul_f32_e32 v250, 0xbfb8aa3b, v242
	v_mul_f32_e32 v251, 0xbfb8aa3b, v243
	v_exp_f32_e32 v248, v248
	v_exp_f32_e32 v249, v249
	v_exp_f32_e32 v250, v250
	v_exp_f32_e32 v251, v251
	v_add_f32_e32 v248, 1.0, v248
	v_add_f32_e32 v249, 1.0, v249
	v_add_f32_e32 v250, 1.0, v250
	v_add_f32_e32 v251, 1.0, v251
	v_rcp_f32_e32 v248, v248
	v_rcp_f32_e32 v249, v249
	v_rcp_f32_e32 v250, v250
	v_rcp_f32_e32 v251, v251
	v_mul_f32_e32 v248, v240, v248
	v_mul_f32_e32 v249, v241, v249
	v_mul_f32_e32 v250, v242, v250
	v_mul_f32_e32 v251, v243, v251
	v_mul_f32_e32 v248, v248, v244
	v_mul_f32_e32 v249, v249, v245
	v_mul_f32_e32 v250, v250, v246
	v_mul_f32_e32 v251, v251, v247
	v_cvt_pk_bf16_f32 v112, v248, v249
	v_cvt_pk_bf16_f32 v113, v250, v251
	v_mov_b32_e32 v110, v230
	v_mov_b32_e32 v111, v231
	s_add_u32 s58, s30, 0x42000
	s_addc_u32 s59, s31, 0
	global_store_dwordx4 v252, v[110:113], s[58:59]
	v_and_b32_e32 v240, 15, v194
	v_add_u32_e32 v240, 1, v240
	v_and_b32_e32 v240, 16, v240
	v_lshl_add_u32 v240, v240, 4, v205
	ds_read_b128 v[190:193], v240 offset:16
	ds_read_b128 v[208:211], v240 offset:144
	s_waitcnt lgkmcnt(0)
; __device__ __forceinline__ unsigned cvt_pk_bf16(float lo, float hi) { f32x2_t_ v = {lo, hi}; bf16x2_t_ b = __builtin_convertvector(v, bf16x2_t_); return __builtin_bit_cast(unsigned, b); }
; __device__ __forceinline__ float dpp_ror1(float v) { return __builtin_bit_cast(float, __builtin_amdgcn_update_dpp(0, __builtin_bit_cast(int, v), 0x121, 0xf, 0xf, false)); }
; __device__ __forceinline__ float dpp_ror2(float v) { return __builtin_bit_cast(float, __builtin_amdgcn_update_dpp(0, __builtin_bit_cast(int, v), 0x122, 0xf, 0xf, false)); }
;     __device__ __forceinline__ void operator()(const f32x4 (&acc)[2][2][4][2], const Unit& u, int wr, int wc, int fr, int fq) const {
;     ...
;                 for (int m = 0; m < 4; ++m) {
;                     float cv[2][4];
; #pragma unroll
;                     for (int bj = 0; bj < 2; ++bj)
; #pragma unroll
;                         for (int e = 0; e < 4; ++e) {
;                             const float x = acc[ai][bj][m][n][e];
;                             const float r1s = dpp_ror1(x), r2s = dpp_ror2(x);
;                             float r1p, r2p;
;                             if (m > 0) { const float xp = acc[ai][bj][m > 0 ? m - 1 : 0][n][e]; r1p = dpp_ror1(xp); r2p = dpp_ror2(xp); }
;                             else { r1p = h1[bj][e]; r2p = (fr == 0) ? h2[bj][e] : h1[bj][e]; }
;                             const float p1 = (fr == 0) ? r1p : r1s, p2 = (fr < 2) ? r2p : r2s;
;                             cv[bj][e] = wgt[0][bj][e] * p2 + wgt[1][bj][e] * p1 + wgt[2][bj][e] * x;
;                         }
;                     const int r = u.pm * BM + ai * HALF + wr * 64 + m * 16 + fr;
;                     if (top && m == 0 && fr < 2) {
; #pragma unroll
;                         for (int bj = 0; bj < 2; ++bj) *(f32x4*)(hb + fr * 256 + bj * 128 + 4 * n) = acc[0][bj][0][n];
;                     } else {
;                         float o[4];
; #pragma unroll
;                         for (int c = 0; c < 4; ++c) { const float g = cv[0][c]; o[c] = g * __builtin_amdgcn_rcpf(1.0f + __expf(-g)) * cv[1][c]; }
;                         u32x2 w; w.x = cvt_pk_bf16(o[0], o[1]); w.y = cvt_pk_bf16(o[2], o[3]);
;                         *(u32x2*)(act + (size_t)r * 2816 + colj + 4 * n) = w;
;                     }
	v_mul_f32_e32 v240, v146, v38
	v_mul_f32_e32 v241, v147, v39
	v_mul_f32_e32 v242, v148, v40
	v_mul_f32_e32 v243, v149, v41
	v_fmac_f32_dpp v240, v38, v138 row_shr:1 row_mask:0xf bank_mask:0xf bound_ctrl:1
	v_fmac_f32_dpp v241, v39, v139 row_shr:1 row_mask:0xf bank_mask:0xf bound_ctrl:1
	v_fmac_f32_dpp v242, v40, v140 row_shr:1 row_mask:0xf bank_mask:0xf bound_ctrl:1
	v_fmac_f32_dpp v243, v41, v141 row_shr:1 row_mask:0xf bank_mask:0xf bound_ctrl:1
	v_fmac_f32_dpp v240, v38, v130 row_shr:2 row_mask:0xf bank_mask:0xf bound_ctrl:1
	v_fmac_f32_dpp v241, v39, v131 row_shr:2 row_mask:0xf bank_mask:0xf bound_ctrl:1
	v_fmac_f32_dpp v242, v40, v132 row_shr:2 row_mask:0xf bank_mask:0xf bound_ctrl:1
	v_fmac_f32_dpp v243, v41, v133 row_shr:2 row_mask:0xf bank_mask:0xf bound_ctrl:1
	v_fmac_f32_dpp v240, v190, v154 row_ror:1 row_mask:0xf bank_mask:0xf
	v_fmac_f32_dpp v241, v191, v155 row_ror:1 row_mask:0xf bank_mask:0xf
	v_fmac_f32_dpp v242, v192, v156 row_ror:1 row_mask:0xf bank_mask:0xf
	v_fmac_f32_dpp v243, v193, v157 row_ror:1 row_mask:0xf bank_mask:0xf
	v_fmac_f32_dpp v240, v190, v162 row_ror:2 row_mask:0xf bank_mask:0xf
	v_fmac_f32_dpp v241, v191, v163 row_ror:2 row_mask:0xf bank_mask:0xf
	v_fmac_f32_dpp v242, v192, v164 row_ror:2 row_mask:0xf bank_mask:0xf
	v_fmac_f32_dpp v243, v193, v165 row_ror:2 row_mask:0xf bank_mask:0xf
	v_mul_f32_e32 v244, v150, v34
	v_mul_f32_e32 v245, v151, v35
	v_mul_f32_e32 v246, v152, v36
	v_mul_f32_e32 v247, v153, v37
	v_fmac_f32_dpp v244, v34, v142 row_shr:1 row_mask:0xf bank_mask:0xf bound_ctrl:1
	v_fmac_f32_dpp v245, v35, v143 row_shr:1 row_mask:0xf bank_mask:0xf bound_ctrl:1
	v_fmac_f32_dpp v246, v36, v144 row_shr:1 row_mask:0xf bank_mask:0xf bound_ctrl:1
	v_fmac_f32_dpp v247, v37, v145 row_shr:1 row_mask:0xf bank_mask:0xf bound_ctrl:1
	v_fmac_f32_dpp v244, v34, v134 row_shr:2 row_mask:0xf bank_mask:0xf bound_ctrl:1
	v_fmac_f32_dpp v245, v35, v135 row_shr:2 row_mask:0xf bank_mask:0xf bound_ctrl:1
	v_fmac_f32_dpp v246, v36, v136 row_shr:2 row_mask:0xf bank_mask:0xf bound_ctrl:1
	v_fmac_f32_dpp v247, v37, v137 row_shr:2 row_mask:0xf bank_mask:0xf bound_ctrl:1
	v_fmac_f32_dpp v244, v208, v158 row_ror:1 row_mask:0xf bank_mask:0xf
	v_fmac_f32_dpp v245, v209, v159 row_ror:1 row_mask:0xf bank_mask:0xf
	v_fmac_f32_dpp v246, v210, v160 row_ror:1 row_mask:0xf bank_mask:0xf
	v_fmac_f32_dpp v247, v211, v161 row_ror:1 row_mask:0xf bank_mask:0xf
	v_fmac_f32_dpp v244, v208, v166 row_ror:2 row_mask:0xf bank_mask:0xf
	v_fmac_f32_dpp v245, v209, v167 row_ror:2 row_mask:0xf bank_mask:0xf
	v_fmac_f32_dpp v246, v210, v168 row_ror:2 row_mask:0xf bank_mask:0xf
	v_fmac_f32_dpp v247, v211, v169 row_ror:2 row_mask:0xf bank_mask:0xf
	v_mul_f32_e32 v248, 0xbfb8aa3b, v240
	v_mul_f32_e32 v249, 0xbfb8aa3b, v241
	v_mul_f32_e32 v250, 0xbfb8aa3b, v242
	v_mul_f32_e32 v251, 0xbfb8aa3b, v243
	v_exp_f32_e32 v248, v248
	v_exp_f32_e32 v249, v249
	v_exp_f32_e32 v250, v250
	v_exp_f32_e32 v251, v251
	v_add_f32_e32 v248, 1.0, v248
	v_add_f32_e32 v249, 1.0, v249
	v_add_f32_e32 v250, 1.0, v250
	v_add_f32_e32 v251, 1.0, v251
	v_rcp_f32_e32 v248, v248
	v_rcp_f32_e32 v249, v249
	v_rcp_f32_e32 v250, v250
	v_rcp_f32_e32 v251, v251
	v_mul_f32_e32 v248, v240, v248
	v_mul_f32_e32 v249, v241, v249
	v_mul_f32_e32 v250, v242, v250
	v_mul_f32_e32 v251, v243, v251
	v_mul_f32_e32 v248, v248, v244
	v_mul_f32_e32 v249, v249, v245
	v_mul_f32_e32 v250, v250, v246
	v_mul_f32_e32 v251, v251, v247
	v_cvt_pk_bf16_f32 v116, v248, v249
	v_cvt_pk_bf16_f32 v117, v250, v251
	v_mov_b32_e32 v114, v232
	v_mov_b32_e32 v115, v233
	s_add_u32 s58, s30, 0xb0000
	s_addc_u32 s59, s31, 0
	global_store_dwordx4 v252, v[114:117], s[58:59]
	v_mul_f32_e32 v240, v146, v30
	v_mul_f32_e32 v241, v147, v31
	v_mul_f32_e32 v242, v148, v32
	v_mul_f32_e32 v243, v149, v33
	v_fmac_f32_dpp v240, v30, v138 row_shr:1 row_mask:0xf bank_mask:0xf bound_ctrl:1
	v_fmac_f32_dpp v241, v31, v139 row_shr:1 row_mask:0xf bank_mask:0xf bound_ctrl:1
	v_fmac_f32_dpp v242, v32, v140 row_shr:1 row_mask:0xf bank_mask:0xf bound_ctrl:1
	v_fmac_f32_dpp v243, v33, v141 row_shr:1 row_mask:0xf bank_mask:0xf bound_ctrl:1
	v_fmac_f32_dpp v240, v30, v130 row_shr:2 row_mask:0xf bank_mask:0xf bound_ctrl:1
	v_fmac_f32_dpp v241, v31, v131 row_shr:2 row_mask:0xf bank_mask:0xf bound_ctrl:1
	v_fmac_f32_dpp v242, v32, v132 row_shr:2 row_mask:0xf bank_mask:0xf bound_ctrl:1
	v_fmac_f32_dpp v243, v33, v133 row_shr:2 row_mask:0xf bank_mask:0xf bound_ctrl:1
	v_fmac_f32_dpp v240, v38, v154 row_ror:1 row_mask:0xf bank_mask:0xf
	v_fmac_f32_dpp v241, v39, v155 row_ror:1 row_mask:0xf bank_mask:0xf
	v_fmac_f32_dpp v242, v40, v156 row_ror:1 row_mask:0xf bank_mask:0xf
	v_fmac_f32_dpp v243, v41, v157 row_ror:1 row_mask:0xf bank_mask:0xf
	v_fmac_f32_dpp v240, v38, v162 row_ror:2 row_mask:0xf bank_mask:0xf
	v_fmac_f32_dpp v241, v39, v163 row_ror:2 row_mask:0xf bank_mask:0xf
	v_fmac_f32_dpp v242, v40, v164 row_ror:2 row_mask:0xf bank_mask:0xf
	v_fmac_f32_dpp v243, v41, v165 row_ror:2 row_mask:0xf bank_mask:0xf
	v_mul_f32_e32 v244, v150, v26
	v_mul_f32_e32 v245, v151, v27
	v_mul_f32_e32 v246, v152, v28
	v_mul_f32_e32 v247, v153, v29
	v_fmac_f32_dpp v244, v26, v142 row_shr:1 row_mask:0xf bank_mask:0xf bound_ctrl:1
	v_fmac_f32_dpp v245, v27, v143 row_shr:1 row_mask:0xf bank_mask:0xf bound_ctrl:1
	v_fmac_f32_dpp v246, v28, v144 row_shr:1 row_mask:0xf bank_mask:0xf bound_ctrl:1
	v_fmac_f32_dpp v247, v29, v145 row_shr:1 row_mask:0xf bank_mask:0xf bound_ctrl:1
	v_fmac_f32_dpp v244, v26, v134 row_shr:2 row_mask:0xf bank_mask:0xf bound_ctrl:1
	v_fmac_f32_dpp v245, v27, v135 row_shr:2 row_mask:0xf bank_mask:0xf bound_ctrl:1
	v_fmac_f32_dpp v246, v28, v136 row_shr:2 row_mask:0xf bank_mask:0xf bound_ctrl:1
; __device__ __forceinline__ unsigned cvt_pk_bf16(float lo, float hi) { f32x2_t_ v = {lo, hi}; bf16x2_t_ b = __builtin_convertvector(v, bf16x2_t_); return __builtin_bit_cast(unsigned, b); }
; __device__ __forceinline__ float dpp_ror1(float v) { return __builtin_bit_cast(float, __builtin_amdgcn_update_dpp(0, __builtin_bit_cast(int, v), 0x121, 0xf, 0xf, false)); }
; __device__ __forceinline__ float dpp_ror2(float v) { return __builtin_bit_cast(float, __builtin_amdgcn_update_dpp(0, __builtin_bit_cast(int, v), 0x122, 0xf, 0xf, false)); }
;     __device__ __forceinline__ void operator()(const f32x4 (&acc)[2][2][4][2], const Unit& u, int wr, int wc, int fr, int fq) const {
;     ...
;                 for (int m = 0; m < 4; ++m) {
;                     float cv[2][4];
; #pragma unroll
;                     for (int bj = 0; bj < 2; ++bj)
; #pragma unroll
;                         for (int e = 0; e < 4; ++e) {
;                             const float x = acc[ai][bj][m][n][e];
;                             const float r1s = dpp_ror1(x), r2s = dpp_ror2(x);
;                             float r1p, r2p;
;                             if (m > 0) { const float xp = acc[ai][bj][m > 0 ? m - 1 : 0][n][e]; r1p = dpp_ror1(xp); r2p = dpp_ror2(xp); }
;                             else { r1p = h1[bj][e]; r2p = (fr == 0) ? h2[bj][e] : h1[bj][e]; }
;                             const float p1 = (fr == 0) ? r1p : r1s, p2 = (fr < 2) ? r2p : r2s;
;                             cv[bj][e] = wgt[0][bj][e] * p2 + wgt[1][bj][e] * p1 + wgt[2][bj][e] * x;
;                         }
;                     const int r = u.pm * BM + ai * HALF + wr * 64 + m * 16 + fr;
;                     if (top && m == 0 && fr < 2) {
; #pragma unroll
;                         for (int bj = 0; bj < 2; ++bj) *(f32x4*)(hb + fr * 256 + bj * 128 + 4 * n) = acc[0][bj][0][n];
;                     } else {
;                         float o[4];
; #pragma unroll
;                         for (int c = 0; c < 4; ++c) { const float g = cv[0][c]; o[c] = g * __builtin_amdgcn_rcpf(1.0f + __expf(-g)) * cv[1][c]; }
;                         u32x2 w; w.x = cvt_pk_bf16(o[0], o[1]); w.y = cvt_pk_bf16(o[2], o[3]);
;                         *(u32x2*)(act + (size_t)r * 2816 + colj + 4 * n) = w;
;                     }
	v_fmac_f32_dpp v247, v29, v137 row_shr:2 row_mask:0xf bank_mask:0xf bound_ctrl:1
	v_fmac_f32_dpp v244, v34, v158 row_ror:1 row_mask:0xf bank_mask:0xf
	v_fmac_f32_dpp v245, v35, v159 row_ror:1 row_mask:0xf bank_mask:0xf
	v_fmac_f32_dpp v246, v36, v160 row_ror:1 row_mask:0xf bank_mask:0xf
	v_fmac_f32_dpp v247, v37, v161 row_ror:1 row_mask:0xf bank_mask:0xf
	v_fmac_f32_dpp v244, v34, v166 row_ror:2 row_mask:0xf bank_mask:0xf
	v_fmac_f32_dpp v245, v35, v167 row_ror:2 row_mask:0xf bank_mask:0xf
	v_fmac_f32_dpp v246, v36, v168 row_ror:2 row_mask:0xf bank_mask:0xf
	v_fmac_f32_dpp v247, v37, v169 row_ror:2 row_mask:0xf bank_mask:0xf
	v_mul_f32_e32 v248, 0xbfb8aa3b, v240
	v_mul_f32_e32 v249, 0xbfb8aa3b, v241
	v_mul_f32_e32 v250, 0xbfb8aa3b, v242
	v_mul_f32_e32 v251, 0xbfb8aa3b, v243
	v_exp_f32_e32 v248, v248
	v_exp_f32_e32 v249, v249
	v_exp_f32_e32 v250, v250
	v_exp_f32_e32 v251, v251
	v_add_f32_e32 v248, 1.0, v248
	v_add_f32_e32 v249, 1.0, v249
	v_add_f32_e32 v250, 1.0, v250
	v_add_f32_e32 v251, 1.0, v251
	v_rcp_f32_e32 v248, v248
	v_rcp_f32_e32 v249, v249
	v_rcp_f32_e32 v250, v250
	v_rcp_f32_e32 v251, v251
	v_mul_f32_e32 v248, v240, v248
	v_mul_f32_e32 v249, v241, v249
	v_mul_f32_e32 v250, v242, v250
	v_mul_f32_e32 v251, v243, v251
	v_mul_f32_e32 v248, v248, v244
	v_mul_f32_e32 v249, v249, v245
	v_mul_f32_e32 v250, v250, v246
	v_mul_f32_e32 v251, v251, v247
	v_cvt_pk_bf16_f32 v120, v248, v249
	v_cvt_pk_bf16_f32 v121, v250, v251
	v_mov_b32_e32 v118, v234
	v_mov_b32_e32 v119, v235
	s_add_u32 s58, s30, 0xc6000
	s_addc_u32 s59, s31, 0
	global_store_dwordx4 v252, v[118:121], s[58:59]
	v_mul_f32_e32 v240, v146, v22
	v_mul_f32_e32 v241, v147, v23
	v_mul_f32_e32 v242, v148, v24
	v_mul_f32_e32 v243, v149, v25
	v_fmac_f32_dpp v240, v22, v138 row_shr:1 row_mask:0xf bank_mask:0xf bound_ctrl:1
	v_fmac_f32_dpp v241, v23, v139 row_shr:1 row_mask:0xf bank_mask:0xf bound_ctrl:1
	v_fmac_f32_dpp v242, v24, v140 row_shr:1 row_mask:0xf bank_mask:0xf bound_ctrl:1
	v_fmac_f32_dpp v243, v25, v141 row_shr:1 row_mask:0xf bank_mask:0xf bound_ctrl:1
	v_fmac_f32_dpp v240, v22, v130 row_shr:2 row_mask:0xf bank_mask:0xf bound_ctrl:1
	v_fmac_f32_dpp v241, v23, v131 row_shr:2 row_mask:0xf bank_mask:0xf bound_ctrl:1
	v_fmac_f32_dpp v242, v24, v132 row_shr:2 row_mask:0xf bank_mask:0xf bound_ctrl:1
	v_fmac_f32_dpp v243, v25, v133 row_shr:2 row_mask:0xf bank_mask:0xf bound_ctrl:1
	v_fmac_f32_dpp v240, v30, v154 row_ror:1 row_mask:0xf bank_mask:0xf
	v_fmac_f32_dpp v241, v31, v155 row_ror:1 row_mask:0xf bank_mask:0xf
	v_fmac_f32_dpp v242, v32, v156 row_ror:1 row_mask:0xf bank_mask:0xf
	v_fmac_f32_dpp v243, v33, v157 row_ror:1 row_mask:0xf bank_mask:0xf
	v_fmac_f32_dpp v240, v30, v162 row_ror:2 row_mask:0xf bank_mask:0xf
	v_fmac_f32_dpp v241, v31, v163 row_ror:2 row_mask:0xf bank_mask:0xf
	v_fmac_f32_dpp v242, v32, v164 row_ror:2 row_mask:0xf bank_mask:0xf
	v_fmac_f32_dpp v243, v33, v165 row_ror:2 row_mask:0xf bank_mask:0xf
	v_mul_f32_e32 v244, v150, v18
	v_mul_f32_e32 v245, v151, v19
	v_mul_f32_e32 v246, v152, v20
	v_mul_f32_e32 v247, v153, v21
	v_fmac_f32_dpp v244, v18, v142 row_shr:1 row_mask:0xf bank_mask:0xf bound_ctrl:1
	v_fmac_f32_dpp v245, v19, v143 row_shr:1 row_mask:0xf bank_mask:0xf bound_ctrl:1
	v_fmac_f32_dpp v246, v20, v144 row_shr:1 row_mask:0xf bank_mask:0xf bound_ctrl:1
	v_fmac_f32_dpp v247, v21, v145 row_shr:1 row_mask:0xf bank_mask:0xf bound_ctrl:1
	v_fmac_f32_dpp v244, v18, v134 row_shr:2 row_mask:0xf bank_mask:0xf bound_ctrl:1
	v_fmac_f32_dpp v245, v19, v135 row_shr:2 row_mask:0xf bank_mask:0xf bound_ctrl:1
	v_fmac_f32_dpp v246, v20, v136 row_shr:2 row_mask:0xf bank_mask:0xf bound_ctrl:1
	v_fmac_f32_dpp v247, v21, v137 row_shr:2 row_mask:0xf bank_mask:0xf bound_ctrl:1
	v_fmac_f32_dpp v244, v26, v158 row_ror:1 row_mask:0xf bank_mask:0xf
	v_fmac_f32_dpp v245, v27, v159 row_ror:1 row_mask:0xf bank_mask:0xf
	v_fmac_f32_dpp v246, v28, v160 row_ror:1 row_mask:0xf bank_mask:0xf
	v_fmac_f32_dpp v247, v29, v161 row_ror:1 row_mask:0xf bank_mask:0xf
	v_fmac_f32_dpp v244, v26, v166 row_ror:2 row_mask:0xf bank_mask:0xf
	v_fmac_f32_dpp v245, v27, v167 row_ror:2 row_mask:0xf bank_mask:0xf
	v_fmac_f32_dpp v246, v28, v168 row_ror:2 row_mask:0xf bank_mask:0xf
	v_fmac_f32_dpp v247, v29, v169 row_ror:2 row_mask:0xf bank_mask:0xf
	v_mul_f32_e32 v248, 0xbfb8aa3b, v240
	v_mul_f32_e32 v249, 0xbfb8aa3b, v241
	v_mul_f32_e32 v250, 0xbfb8aa3b, v242
	v_mul_f32_e32 v251, 0xbfb8aa3b, v243
; __device__ __forceinline__ unsigned cvt_pk_bf16(float lo, float hi) { f32x2_t_ v = {lo, hi}; bf16x2_t_ b = __builtin_convertvector(v, bf16x2_t_); return __builtin_bit_cast(unsigned, b); }
; __device__ __forceinline__ float dpp_ror1(float v) { return __builtin_bit_cast(float, __builtin_amdgcn_update_dpp(0, __builtin_bit_cast(int, v), 0x121, 0xf, 0xf, false)); }
; __device__ __forceinline__ float dpp_ror2(float v) { return __builtin_bit_cast(float, __builtin_amdgcn_update_dpp(0, __builtin_bit_cast(int, v), 0x122, 0xf, 0xf, false)); }
;     __device__ __forceinline__ void operator()(const f32x4 (&acc)[2][2][4][2], const Unit& u, int wr, int wc, int fr, int fq) const {
;     ...
;                 for (int m = 0; m < 4; ++m) {
;                     float cv[2][4];
; #pragma unroll
;                     for (int bj = 0; bj < 2; ++bj)
; #pragma unroll
;                         for (int e = 0; e < 4; ++e) {
;                             const float x = acc[ai][bj][m][n][e];
;                             const float r1s = dpp_ror1(x), r2s = dpp_ror2(x);
;                             float r1p, r2p;
;                             if (m > 0) { const float xp = acc[ai][bj][m > 0 ? m - 1 : 0][n][e]; r1p = dpp_ror1(xp); r2p = dpp_ror2(xp); }
;                             else { r1p = h1[bj][e]; r2p = (fr == 0) ? h2[bj][e] : h1[bj][e]; }
;                             const float p1 = (fr == 0) ? r1p : r1s, p2 = (fr < 2) ? r2p : r2s;
;                             cv[bj][e] = wgt[0][bj][e] * p2 + wgt[1][bj][e] * p1 + wgt[2][bj][e] * x;
;                         }
;                     const int r = u.pm * BM + ai * HALF + wr * 64 + m * 16 + fr;
;                     if (top && m == 0 && fr < 2) {
; #pragma unroll
;                         for (int bj = 0; bj < 2; ++bj) *(f32x4*)(hb + fr * 256 + bj * 128 + 4 * n) = acc[0][bj][0][n];
;                     } else {
;                         float o[4];
; #pragma unroll
;                         for (int c = 0; c < 4; ++c) { const float g = cv[0][c]; o[c] = g * __builtin_amdgcn_rcpf(1.0f + __expf(-g)) * cv[1][c]; }
;                         u32x2 w; w.x = cvt_pk_bf16(o[0], o[1]); w.y = cvt_pk_bf16(o[2], o[3]);
;                         *(u32x2*)(act + (size_t)r * 2816 + colj + 4 * n) = w;
;                     }
	v_exp_f32_e32 v248, v248
	v_exp_f32_e32 v249, v249
	v_exp_f32_e32 v250, v250
	v_exp_f32_e32 v251, v251
	v_add_f32_e32 v248, 1.0, v248
	v_add_f32_e32 v249, 1.0, v249
	v_add_f32_e32 v250, 1.0, v250
	v_add_f32_e32 v251, 1.0, v251
	v_rcp_f32_e32 v248, v248
	v_rcp_f32_e32 v249, v249
	v_rcp_f32_e32 v250, v250
	v_rcp_f32_e32 v251, v251
	v_mul_f32_e32 v248, v240, v248
	v_mul_f32_e32 v249, v241, v249
	v_mul_f32_e32 v250, v242, v250
	v_mul_f32_e32 v251, v243, v251
	v_mul_f32_e32 v248, v248, v244
	v_mul_f32_e32 v249, v249, v245
	v_mul_f32_e32 v250, v250, v246
	v_mul_f32_e32 v251, v251, v247
	v_cvt_pk_bf16_f32 v100, v248, v249
	v_cvt_pk_bf16_f32 v101, v250, v251
	v_mov_b32_e32 v98, v236
	v_mov_b32_e32 v99, v237
	s_add_u32 s58, s30, 0xdc000
	s_addc_u32 s59, s31, 0
	global_store_dwordx4 v252, v[98:101], s[58:59]
	v_mul_f32_e32 v240, v146, v10
	v_mul_f32_e32 v241, v147, v11
	v_mul_f32_e32 v242, v148, v12
	v_mul_f32_e32 v243, v149, v13
	v_fmac_f32_dpp v240, v10, v138 row_shr:1 row_mask:0xf bank_mask:0xf bound_ctrl:1
	v_fmac_f32_dpp v241, v11, v139 row_shr:1 row_mask:0xf bank_mask:0xf bound_ctrl:1
	v_fmac_f32_dpp v242, v12, v140 row_shr:1 row_mask:0xf bank_mask:0xf bound_ctrl:1
	v_fmac_f32_dpp v243, v13, v141 row_shr:1 row_mask:0xf bank_mask:0xf bound_ctrl:1
	v_fmac_f32_dpp v240, v10, v130 row_shr:2 row_mask:0xf bank_mask:0xf bound_ctrl:1
	v_fmac_f32_dpp v241, v11, v131 row_shr:2 row_mask:0xf bank_mask:0xf bound_ctrl:1
	v_fmac_f32_dpp v242, v12, v132 row_shr:2 row_mask:0xf bank_mask:0xf bound_ctrl:1
	v_fmac_f32_dpp v243, v13, v133 row_shr:2 row_mask:0xf bank_mask:0xf bound_ctrl:1
	v_fmac_f32_dpp v240, v22, v154 row_ror:1 row_mask:0xf bank_mask:0xf
	v_fmac_f32_dpp v241, v23, v155 row_ror:1 row_mask:0xf bank_mask:0xf
	v_fmac_f32_dpp v242, v24, v156 row_ror:1 row_mask:0xf bank_mask:0xf
	v_fmac_f32_dpp v243, v25, v157 row_ror:1 row_mask:0xf bank_mask:0xf
	v_fmac_f32_dpp v240, v22, v162 row_ror:2 row_mask:0xf bank_mask:0xf
	v_fmac_f32_dpp v241, v23, v163 row_ror:2 row_mask:0xf bank_mask:0xf
	v_fmac_f32_dpp v242, v24, v164 row_ror:2 row_mask:0xf bank_mask:0xf
	v_fmac_f32_dpp v243, v25, v165 row_ror:2 row_mask:0xf bank_mask:0xf
	v_mul_f32_e32 v244, v150, v2
	v_mul_f32_e32 v245, v151, v3
	v_mul_f32_e32 v246, v152, v4
	v_mul_f32_e32 v247, v153, v5
	v_fmac_f32_dpp v244, v2, v142 row_shr:1 row_mask:0xf bank_mask:0xf bound_ctrl:1
	v_fmac_f32_dpp v245, v3, v143 row_shr:1 row_mask:0xf bank_mask:0xf bound_ctrl:1
	v_fmac_f32_dpp v246, v4, v144 row_shr:1 row_mask:0xf bank_mask:0xf bound_ctrl:1
	v_fmac_f32_dpp v247, v5, v145 row_shr:1 row_mask:0xf bank_mask:0xf bound_ctrl:1
	v_fmac_f32_dpp v244, v2, v134 row_shr:2 row_mask:0xf bank_mask:0xf bound_ctrl:1
	v_fmac_f32_dpp v245, v3, v135 row_shr:2 row_mask:0xf bank_mask:0xf bound_ctrl:1
	v_fmac_f32_dpp v246, v4, v136 row_shr:2 row_mask:0xf bank_mask:0xf bound_ctrl:1
	v_fmac_f32_dpp v247, v5, v137 row_shr:2 row_mask:0xf bank_mask:0xf bound_ctrl:1
	v_fmac_f32_dpp v244, v18, v158 row_ror:1 row_mask:0xf bank_mask:0xf
	v_fmac_f32_dpp v245, v19, v159 row_ror:1 row_mask:0xf bank_mask:0xf
	v_fmac_f32_dpp v246, v20, v160 row_ror:1 row_mask:0xf bank_mask:0xf
	v_fmac_f32_dpp v247, v21, v161 row_ror:1 row_mask:0xf bank_mask:0xf
	v_fmac_f32_dpp v244, v18, v166 row_ror:2 row_mask:0xf bank_mask:0xf
	v_fmac_f32_dpp v245, v19, v167 row_ror:2 row_mask:0xf bank_mask:0xf
	v_fmac_f32_dpp v246, v20, v168 row_ror:2 row_mask:0xf bank_mask:0xf
	v_fmac_f32_dpp v247, v21, v169 row_ror:2 row_mask:0xf bank_mask:0xf
	v_mul_f32_e32 v248, 0xbfb8aa3b, v240
	v_mul_f32_e32 v249, 0xbfb8aa3b, v241
	v_mul_f32_e32 v250, 0xbfb8aa3b, v242
	v_mul_f32_e32 v251, 0xbfb8aa3b, v243
	v_exp_f32_e32 v248, v248
	v_exp_f32_e32 v249, v249
	v_exp_f32_e32 v250, v250
	v_exp_f32_e32 v251, v251
	v_add_f32_e32 v248, 1.0, v248
	v_add_f32_e32 v249, 1.0, v249
	v_add_f32_e32 v250, 1.0, v250
	v_add_f32_e32 v251, 1.0, v251
	v_rcp_f32_e32 v248, v248
	v_rcp_f32_e32 v249, v249
	v_rcp_f32_e32 v250, v250
	v_rcp_f32_e32 v251, v251
	v_mul_f32_e32 v248, v240, v248
	v_mul_f32_e32 v249, v241, v249
	v_mul_f32_e32 v250, v242, v250
	v_mul_f32_e32 v251, v243, v251
	v_mul_f32_e32 v248, v248, v244
	v_mul_f32_e32 v249, v249, v245
	v_mul_f32_e32 v250, v250, v246
	v_mul_f32_e32 v251, v251, v247
	v_cvt_pk_bf16_f32 v104, v248, v249
	v_cvt_pk_bf16_f32 v105, v250, v251
	v_mov_b32_e32 v102, v238
	v_mov_b32_e32 v103, v239
	s_add_u32 s58, s30, 0xf2000
	s_addc_u32 s59, s31, 0
	global_store_dwordx4 v252, v[102:105], s[58:59]
